# FA lazy-rescale decision shortened in all five loops: common case falls through after the first wave-uniform test, rare max-update/rescale path moved out of line (same arithmetic)
# baseline (speedup 1.0000x reference)
; #define FA_SBAR() __builtin_amdgcn_sched_barrier(0)
; __device__ __forceinline__ void mask_bits(f32x16& p0, f32x16& p1, unsigned lo, unsigned hi_w, int hi) {
;     const unsigned a = lo >> (4 * hi), b = hi_w >> (4 * hi); const unsigned NEGB = 0xFF800000u;
; #pragma unroll
;     for (int r = 0; r < 16; ++r) { const int c = (r & 3) + 8 * (r >> 2);
;         const unsigned ma = (unsigned)__builtin_amdgcn_sbfe((int)a, c, 1), mb = (unsigned)__builtin_amdgcn_sbfe((int)b, c, 1);
;         const float x0 = p0[r], x1 = p1[r];
;         p0[r] = __uint_as_float((__float_as_uint(x0) & ma) | (NEGB & ~ma));
;         p1[r] = __uint_as_float((__float_as_uint(x1) & mb) | (NEGB & ~mb)); }
; }
; __device__ __forceinline__ float max3f(float a, float b, float c) { return __builtin_fmaxf(__builtin_fmaxf(a, b), c); }
; __device__ __forceinline__ void partialSM(f32x16& p0, f32x16& p1, float& m_reg, float& mn, float& alpha, const float sc, const float C2) {
;     float pmax = max3f(p0[0], p0[1], p0[2]);
; #pragma unroll
;     for (int r = 3; r < 15; r += 2) pmax = max3f(pmax, p0[r], p0[r + 1]);
;     pmax = max3f(pmax, p0[15], p1[0]);
; #pragma unroll
;     for (int r = 1; r < 15; r += 2) pmax = max3f(pmax, p1[r], p1[r + 1]);
;     pmax = fmaxf(pmax, p1[15]);
;     { auto rr = __builtin_amdgcn_permlane32_swap(__float_as_uint(pmax), __float_as_uint(pmax), false, false);
;       pmax = fmaxf(__uint_as_float(rr[0]), __uint_as_float(rr[1])); }
;     if (__builtin_expect(__all((pmax - m_reg) * sc <= 8.0f), 1)) { mn = m_reg; alpha = 1.f; }
;     else { mn = fmaxf(m_reg, pmax); alpha = __builtin_amdgcn_exp2f((m_reg - mn) * C2); m_reg = mn; }
; template <bool MLA>
; __device__ __forceinline__ void qkt2(f32x16& p0, f32x16& p1, const LAS char* lds, int kboff, int kroff, int r32, int hi, const half8* qr) {
;     ...
; #pragma unroll
;     for (int r = 0; r < 16; ++r) { p0[r] = 0.f; p1[r] = 0.f; }
;     QK_LD(fa0, fa1, 0); FA_SBAR();
;     QK_LD(fb0, fb1, 1); FA_SBAR(); QK_MM(fa0, fa1, 0); FA_SBAR();
;     QK_LD(fa0, fa1, 2); FA_SBAR(); QK_MM(fb0, fb1, 1); FA_SBAR();
;     QK_LD(fb0, fb1, 3); FA_SBAR(); QK_MM(fa0, fa1, 2); FA_SBAR();
;     if constexpr (NG == 6) {
;         QK_LD(fa0, fa1, 4); FA_SBAR(); QK_MM(fb0, fb1, 3); FA_SBAR();
;         QK_LD(fb0, fb1, 5); FA_SBAR(); QK_MM(fa0, fa1, 4); FA_SBAR();
;         QK_MM(fb0, fb1, 5);
;     } else QK_MM(fb0, fb1, 3);
;     ...
; }
.LBB0_4934:
	s_and_b32 s8, s24, 1
	v_mov_b32_e32 v2, s8
	s_cmp_gt_i32 s22, s17
	s_cbranch_scc1 .LBB0_4940
	v_lshlrev_b32_e32 v2, 14, v2
	v_add_u32_e32 v6, v180, v2
	v_add_u32_e32 v196, v6, v181
	v_add_u32_e32 v197, v6, v182
	v_add_u32_e32 v208, v6, v183
	v_add_u32_e32 v209, v6, v184
	ds_read_b128 v[6:9], v196 offset:32768
	ds_read_b128 v[10:13], v196 offset:40960
	ds_read_b128 v[14:17], v197 offset:32768
	ds_read_b128 v[188:191], v197 offset:40960
	ds_read_b128 v[192:195], v208 offset:32768
	ds_read_b128 v[204:207], v208 offset:40960
	ds_read_b128 v[220:223], v209 offset:32768
	ds_read_b128 v[224:227], v209 offset:40960
	s_waitcnt lgkmcnt(7)
	v_mfma_f32_32x32x16_f16 v[82:97], v[6:9], v[130:133], 0
	s_waitcnt lgkmcnt(6)
	v_mfma_f32_32x32x16_f16 v[98:113], v[10:13], v[130:133], 0
	s_waitcnt lgkmcnt(5)
	v_mfma_f32_32x32x16_f16 v[82:97], v[14:17], v[134:137], v[82:97]
	s_waitcnt lgkmcnt(4)
	v_mfma_f32_32x32x16_f16 v[98:113], v[188:191], v[134:137], v[98:113]
	ds_read_b128 v[6:9], v196 offset:32896
	ds_read_b128 v[10:13], v196 offset:41088
	ds_read_b128 v[14:17], v197 offset:32896
	ds_read_b128 v[188:191], v197 offset:41088
	s_waitcnt lgkmcnt(7)
	v_mfma_f32_32x32x16_f16 v[82:97], v[192:195], v[138:141], v[82:97]
	s_waitcnt lgkmcnt(6)
	v_mfma_f32_32x32x16_f16 v[98:113], v[204:207], v[138:141], v[98:113]
	s_waitcnt lgkmcnt(5)
	v_mfma_f32_32x32x16_f16 v[82:97], v[220:223], v[142:145], v[82:97]
	s_waitcnt lgkmcnt(4)
	v_mfma_f32_32x32x16_f16 v[98:113], v[224:227], v[142:145], v[98:113]
	ds_read_b128 v[192:195], v208 offset:32896
	ds_read_b128 v[204:207], v208 offset:41088
	ds_read_b128 v[220:223], v209 offset:32896
	ds_read_b128 v[224:227], v209 offset:41088
	s_waitcnt lgkmcnt(7)
	v_mfma_f32_32x32x16_f16 v[82:97], v[6:9], v[146:149], v[82:97]
	s_waitcnt lgkmcnt(6)
	v_mfma_f32_32x32x16_f16 v[98:113], v[10:13], v[146:149], v[98:113]
	s_waitcnt lgkmcnt(5)
	v_mfma_f32_32x32x16_f16 v[82:97], v[14:17], v[150:153], v[82:97]
	s_waitcnt lgkmcnt(4)
	v_mfma_f32_32x32x16_f16 v[98:113], v[188:191], v[150:153], v[98:113]
	s_waitcnt lgkmcnt(3)
	v_mfma_f32_32x32x16_f16 v[82:97], v[192:195], v[154:157], v[82:97]
	v_lshrrev_b32_e32 v189, v174, v164
	v_lshrrev_b32_e32 v190, v174, v165
	v_bfe_i32 v6, v189, 0, 1
	v_bfe_i32 v7, v190, 0, 1
	v_bfe_i32 v8, v190, 1, 1
	v_bfe_i32 v9, v190, 2, 1
	v_bfe_i32 v10, v190, 3, 1
	s_waitcnt lgkmcnt(2)
	v_mfma_f32_32x32x16_f16 v[98:113], v[204:207], v[154:157], v[98:113]
	v_bfe_i32 v11, v190, 8, 1
	v_bfe_i32 v12, v190, 9, 1
	v_bfe_i32 v13, v190, 10, 1
	v_bfe_i32 v14, v190, 11, 1
	v_bfe_i32 v15, v190, 16, 1
	v_bfe_i32 v16, v190, 17, 1
	v_bfe_i32 v17, v190, 18, 1
	s_waitcnt lgkmcnt(1)
	v_mfma_f32_32x32x16_f16 v[82:97], v[220:223], v[158:161], v[82:97]
	s_waitcnt lgkmcnt(0)
	v_mfma_f32_32x32x16_f16 v[98:113], v[224:227], v[158:161], v[98:113]
	s_nop 9
	v_bitop3_b32 v188, v82, s36, v6 bitop3:0xe4
	v_bfe_i32 v82, v190, 19, 1
	v_bitop3_b32 v6, v98, s36, v7 bitop3:0xe4
	v_bfe_i32 v7, v189, 1, 1
	v_bitop3_b32 v98, v83, s36, v7 bitop3:0xe4
	v_bitop3_b32 v7, v99, s36, v8 bitop3:0xe4
	v_bfe_i32 v8, v189, 2, 1
	v_bitop3_b32 v99, v84, s36, v8 bitop3:0xe4
	v_bitop3_b32 v8, v100, s36, v9 bitop3:0xe4
	v_bfe_i32 v9, v189, 3, 1
	v_bitop3_b32 v100, v85, s36, v9 bitop3:0xe4
	v_bitop3_b32 v9, v101, s36, v10 bitop3:0xe4
	v_bfe_i32 v10, v189, 8, 1
	v_bitop3_b32 v101, v86, s36, v10 bitop3:0xe4
	v_bitop3_b32 v10, v102, s36, v11 bitop3:0xe4
	v_bfe_i32 v11, v189, 9, 1
	v_bitop3_b32 v87, v87, s36, v11 bitop3:0xe4
	v_bitop3_b32 v11, v103, s36, v12 bitop3:0xe4
	v_bfe_i32 v12, v189, 10, 1
	v_bitop3_b32 v88, v88, s36, v12 bitop3:0xe4
	v_bitop3_b32 v12, v104, s36, v13 bitop3:0xe4
	v_bfe_i32 v13, v189, 11, 1
	v_bitop3_b32 v89, v89, s36, v13 bitop3:0xe4
	v_bitop3_b32 v13, v105, s36, v14 bitop3:0xe4
	v_bfe_i32 v14, v189, 16, 1
	v_bitop3_b32 v90, v90, s36, v14 bitop3:0xe4
	v_bitop3_b32 v14, v106, s36, v15 bitop3:0xe4
	v_bfe_i32 v15, v189, 17, 1
	v_bitop3_b32 v91, v91, s36, v15 bitop3:0xe4
	v_bitop3_b32 v15, v107, s36, v16 bitop3:0xe4
	v_bfe_i32 v16, v189, 18, 1
	v_bitop3_b32 v92, v92, s36, v16 bitop3:0xe4
	v_bitop3_b32 v16, v108, s36, v17 bitop3:0xe4
	v_bfe_i32 v17, v189, 19, 1
	v_bitop3_b32 v93, v93, s36, v17 bitop3:0xe4
	v_bitop3_b32 v17, v109, s36, v82 bitop3:0xe4
	v_bfe_i32 v82, v189, 24, 1
	v_bfe_i32 v83, v190, 24, 1
	v_bitop3_b32 v94, v94, s36, v82 bitop3:0xe4
	v_bitop3_b32 v82, v110, s36, v83 bitop3:0xe4
	v_bfe_i32 v83, v189, 25, 1
	v_bfe_i32 v84, v190, 25, 1
	v_bitop3_b32 v95, v95, s36, v83 bitop3:0xe4
	v_bitop3_b32 v83, v111, s36, v84 bitop3:0xe4
	v_bfe_i32 v84, v189, 26, 1
	v_bfe_i32 v85, v190, 26, 1
	v_bitop3_b32 v96, v96, s36, v84 bitop3:0xe4
	v_bitop3_b32 v84, v112, s36, v85 bitop3:0xe4
	v_bfe_i32 v85, v189, 27, 1
	v_bfe_i32 v86, v190, 27, 1
	v_bitop3_b32 v97, v97, s36, v85 bitop3:0xe4
	v_bitop3_b32 v85, v113, s36, v86 bitop3:0xe4
	v_max_f32_e32 v86, v98, v98
	v_max_f32_e32 v102, v188, v188
	v_max_f32_e32 v86, v102, v86
	v_max3_f32 v86, v86, v99, v100
	v_max3_f32 v86, v86, v101, v87
	v_max3_f32 v86, v86, v88, v89
	v_max3_f32 v86, v86, v90, v91
	v_max3_f32 v86, v86, v92, v93
	v_max3_f32 v86, v86, v94, v95
	v_max3_f32 v86, v86, v96, v97
	v_max3_f32 v86, v86, v6, v7
	v_max3_f32 v86, v86, v8, v9
	v_max3_f32 v86, v86, v10, v11
	v_max3_f32 v86, v86, v12, v13
	v_max3_f32 v86, v86, v14, v15
	v_max3_f32 v86, v86, v16, v17
	v_max3_f32 v86, v86, v82, v83
	v_max3_f32 v86, v86, v84, v85
	v_mov_b32_e32 v102, v86
	s_nop 1
	v_permlane32_swap_b32_e32 v86, v102
	v_max_f32_e32 v86, v86, v102
	v_sub_f32_e32 v102, v86, v186
	v_mul_f32_e32 v103, 0x3db504f3, v102
	v_cmp_ge_f32_e32 vcc, s87, v103
	s_cmp_eq_u64 vcc, exec
	s_cbranch_scc0 .Ldsa_slow
	v_mov_b32_e32 v86, 1.0
; #define FA_SBAR() __builtin_amdgcn_sched_barrier(0)
; #define FA_RD8(S, d0) do { constexpr int b_ = v_rd_off(d0, 0, 0); FA_TRRD(S##l0, b_); FA_TRRD(S##h0, b_ + 2048); FA_TRRD(S##l1, b_ + 4096); FA_TRRD(S##h1, b_ + 6144); FA_TRRD(S##l2, b_ + 8192); FA_TRRD(S##h2, b_ + 10240); FA_TRRD(S##l3, b_ + 12288); FA_TRRD(S##h3, b_ + 14336); } while (0)
; __device__ __forceinline__ void partialSM(f32x16& p0, f32x16& p1, float& m_reg, float& mn, float& alpha, const float sc, const float C2) {
;     ...
;     const float mnL = -mn * C2;
; #pragma unroll
;     for (int r = 0; r < 16; ++r) p0[r] = __builtin_amdgcn_exp2f(fmaf(p0[r], C2, mnL));
; #pragma unroll
;     for (int r = 0; r < 16; ++r) p1[r] = __builtin_amdgcn_exp2f(fmaf(p1[r], C2, mnL));
; }
; __device__ __forceinline__ void finishSM(const f32x16& p0, const f32x16& p1, float alpha, float& l_reg, half8& pa0, half8& pa1, half8& pa2, half8& pa3) {
;     f32x2 s2 = {0.f, 0.f};
; #pragma unroll
;     for (int r = 0; r < 16; r += 2) { s2 += (f32x2){p0[r], p0[r + 1]}; s2 += (f32x2){p1[r], p1[r + 1]}; }
;     float ps = s2[0] + s2[1];
;     { auto rr = __builtin_amdgcn_permlane32_swap(__float_as_uint(ps), __float_as_uint(ps), false, false);
;       ps = __uint_as_float(rr[0]) + __uint_as_float(rr[1]); }
;     l_reg = l_reg * alpha + ps;
;     ...
;     FA_PK4(p0, 0, pa0); FA_PK4(p0, 8, pa1); FA_PK4(p1, 0, pa2); FA_PK4(p1, 8, pa3);
;     ...
; }
; __device__ __forceinline__ void pv_tile2(f32x16* o, int vb0, half8 pa0, half8 pa1, half8 pa2, half8 pa3) {
;     ...
;     s16x4 al0, al1, al2, al3, ah0, ah1, ah2, ah3, bl0, bl1, bl2, bl3, bh0, bh1, bh2, bh3;
;     FA_RD8(a, 0);
;     FA_RD8(b, 1); asm volatile("s_waitcnt lgkmcnt(8)" ::: "memory"); FA_SBAR(); FA_MM4(a, 0); FA_SBAR();
;     FA_RD8(a, 2); asm volatile("s_waitcnt lgkmcnt(8)" ::: "memory"); FA_SBAR(); FA_MM4(b, 1); FA_SBAR();
;     FA_RD8(b, 3); asm volatile("s_waitcnt lgkmcnt(8)" ::: "memory"); FA_SBAR(); FA_MM4(a, 2); FA_SBAR();
;     asm volatile("s_waitcnt lgkmcnt(0)" ::: "memory"); FA_SBAR(); FA_MM4(b, 3);
.Ldsa_fast:
.LBB0_4939:
	v_mul_f32_e32 v193, 0xbe0293ee, v186
	v_fmamk_f32 v6, v6, 0x3e0293ee, v193
	v_exp_f32_e32 v104, v6
	v_fmamk_f32 v6, v7, 0x3e0293ee, v193
	v_exp_f32_e32 v105, v6
	v_fmamk_f32 v6, v8, 0x3e0293ee, v193
	v_exp_f32_e32 v106, v6
	v_fmamk_f32 v6, v9, 0x3e0293ee, v193
	v_exp_f32_e32 v107, v6
	v_fmamk_f32 v6, v10, 0x3e0293ee, v193
	v_exp_f32_e32 v108, v6
	v_fmamk_f32 v6, v11, 0x3e0293ee, v193
	v_exp_f32_e32 v109, v6
	v_fmamk_f32 v6, v12, 0x3e0293ee, v193
	v_exp_f32_e32 v110, v6
	v_fmamk_f32 v6, v13, 0x3e0293ee, v193
	v_exp_f32_e32 v111, v6
	v_fmamk_f32 v6, v14, 0x3e0293ee, v193
	v_exp_f32_e32 v112, v6
	v_fmamk_f32 v6, v15, 0x3e0293ee, v193
	v_fmamk_f32 v102, v188, 0x3e0293ee, v193
	v_fmamk_f32 v98, v98, 0x3e0293ee, v193
	v_exp_f32_e32 v113, v6
	v_fmamk_f32 v6, v16, 0x3e0293ee, v193
	v_exp_f32_e32 v102, v102
	v_exp_f32_e32 v103, v98
	v_exp_f32_e32 v188, v6
	v_fmamk_f32 v6, v17, 0x3e0293ee, v193
	v_fmamk_f32 v98, v99, 0x3e0293ee, v193
	v_fmamk_f32 v99, v100, 0x3e0293ee, v193
	v_exp_f32_e32 v189, v6
	v_fmamk_f32 v6, v82, 0x3e0293ee, v193
	v_exp_f32_e32 v98, v98
	v_exp_f32_e32 v99, v99
	v_exp_f32_e32 v190, v6
	v_fmamk_f32 v6, v83, 0x3e0293ee, v193
	v_fmamk_f32 v100, v101, 0x3e0293ee, v193
	v_fmamk_f32 v87, v87, 0x3e0293ee, v193
	v_exp_f32_e32 v191, v6
	v_fmamk_f32 v6, v84, 0x3e0293ee, v193
	v_exp_f32_e32 v100, v100
	v_exp_f32_e32 v101, v87
	v_fmamk_f32 v87, v88, 0x3e0293ee, v193
	v_exp_f32_e32 v192, v6
	v_pk_add_f32 v[6:7], v[102:103], 0 op_sel_hi:[1,0]
	v_exp_f32_e32 v88, v87
	v_fmamk_f32 v87, v89, 0x3e0293ee, v193
	v_pk_add_f32 v[6:7], v[6:7], v[104:105]
	v_exp_f32_e32 v89, v87
	v_fmamk_f32 v87, v90, 0x3e0293ee, v193
	v_pk_add_f32 v[6:7], v[6:7], v[98:99]
	v_exp_f32_e32 v90, v87
	v_fmamk_f32 v87, v91, 0x3e0293ee, v193
	v_pk_add_f32 v[6:7], v[6:7], v[106:107]
	v_exp_f32_e32 v91, v87
	v_fmamk_f32 v87, v92, 0x3e0293ee, v193
	v_pk_add_f32 v[6:7], v[6:7], v[100:101]
	v_exp_f32_e32 v92, v87
	v_fmamk_f32 v87, v93, 0x3e0293ee, v193
	v_pk_add_f32 v[6:7], v[6:7], v[108:109]
	v_exp_f32_e32 v93, v87
	v_fmamk_f32 v87, v94, 0x3e0293ee, v193
	v_pk_add_f32 v[6:7], v[6:7], v[88:89]
	v_exp_f32_e32 v94, v87
	v_fmamk_f32 v87, v95, 0x3e0293ee, v193
	v_pk_add_f32 v[6:7], v[6:7], v[110:111]
	v_exp_f32_e32 v95, v87
	v_fmamk_f32 v87, v96, 0x3e0293ee, v193
	v_pk_add_f32 v[6:7], v[6:7], v[90:91]
	v_exp_f32_e32 v96, v87
	v_fmamk_f32 v87, v97, 0x3e0293ee, v193
	v_pk_add_f32 v[6:7], v[6:7], v[112:113]
	v_exp_f32_e32 v97, v87
	v_fmac_f32_e32 v193, 0x3e0293ee, v85
	v_pk_add_f32 v[6:7], v[6:7], v[92:93]
	v_exp_f32_e32 v193, v193
	v_pk_add_f32 v[6:7], v[6:7], v[188:189]
	v_cvt_pk_f16_f32 v8, v100, v101
	v_pk_add_f32 v[6:7], v[94:95], v[6:7]
	v_cvt_pk_f16_f32 v9, v88, v89
	v_pk_add_f32 v[6:7], v[190:191], v[6:7]
	v_cvt_pk_f16_f32 v10, v90, v91
	v_pk_add_f32 v[6:7], v[96:97], v[6:7]
	v_cvt_pk_f16_f32 v11, v92, v93
	v_pk_add_f32 v[6:7], v[192:193], v[6:7]
	v_cvt_pk_f16_f32 v12, v94, v95
	v_pk_add_f32 v[6:7], v[6:7], v[6:7] op_sel:[0,1] op_sel_hi:[1,0]
	v_cvt_pk_f16_f32 v13, v96, v97
	v_mov_b32_e32 v7, v6
	s_nop 1
	v_permlane32_swap_b32_e32 v6, v7
	v_add_f32_e32 v194, v6, v7
	v_cvt_pk_f16_f32 v6, v102, v103
	v_cvt_pk_f16_f32 v7, v98, v99
	v_cvt_pk_f16_f32 v14, v104, v105
	v_cvt_pk_f16_f32 v15, v106, v107
	v_cvt_pk_f16_f32 v16, v108, v109
	v_cvt_pk_f16_f32 v17, v110, v111
	v_cvt_pk_f16_f32 v82, v112, v113
	v_cvt_pk_f16_f32 v83, v188, v189
	v_cvt_pk_f16_f32 v84, v190, v191
	v_cvt_pk_f16_f32 v85, v192, v193
	v_fmac_f32_e32 v194, v187, v86
	v_permlane32_swap_b32_e32 v6, v8
	v_permlane32_swap_b32_e32 v7, v9
	v_permlane32_swap_b32_e32 v10, v12
	v_permlane32_swap_b32_e32 v11, v13
	v_permlane32_swap_b32_e32 v14, v16
	v_permlane32_swap_b32_e32 v15, v17
	v_permlane32_swap_b32_e32 v82, v84
	v_permlane32_swap_b32_e32 v83, v85
	v_add_u32_e32 v2, v185, v2
	ds_read_b64_tr_b16 v[86:87], v2 offset:0
	ds_read_b64_tr_b16 v[88:89], v2 offset:0x800
	ds_read_b64_tr_b16 v[90:91], v2 offset:0x1000
	ds_read_b64_tr_b16 v[92:93], v2 offset:0x1800
	ds_read_b64_tr_b16 v[94:95], v2 offset:0x2000
	ds_read_b64_tr_b16 v[96:97], v2 offset:0x2800
	ds_read_b64_tr_b16 v[98:99], v2 offset:0x3000
	ds_read_b64_tr_b16 v[100:101], v2 offset:0x3800
	ds_read_b64_tr_b16 v[102:103], v2 offset:0x200
	ds_read_b64_tr_b16 v[104:105], v2 offset:0xa00
	ds_read_b64_tr_b16 v[106:107], v2 offset:0x1200
	ds_read_b64_tr_b16 v[108:109], v2 offset:0x1a00
	ds_read_b64_tr_b16 v[110:111], v2 offset:0x2200
	ds_read_b64_tr_b16 v[112:113], v2 offset:0x2a00
	ds_read_b64_tr_b16 v[188:189], v2 offset:0x3200
	ds_read_b64_tr_b16 v[190:191], v2 offset:0x3a00
	s_waitcnt lgkmcnt(8)
	s_nop 0
	v_mfma_f32_32x32x16_f16 v[66:81], v[6:9], v[86:89], v[66:81]
	v_mfma_f32_32x32x16_f16 v[66:81], v[10:13], v[90:93], v[66:81]
	v_mfma_f32_32x32x16_f16 v[66:81], v[14:17], v[94:97], v[66:81]
	v_mfma_f32_32x32x16_f16 v[66:81], v[82:85], v[98:101], v[66:81]
	ds_read_b64_tr_b16 v[86:87], v2 offset:0x400
	ds_read_b64_tr_b16 v[88:89], v2 offset:0xc00
	ds_read_b64_tr_b16 v[90:91], v2 offset:0x1400
	ds_read_b64_tr_b16 v[92:93], v2 offset:0x1c00
	ds_read_b64_tr_b16 v[94:95], v2 offset:0x2400
	ds_read_b64_tr_b16 v[96:97], v2 offset:0x2c00
	ds_read_b64_tr_b16 v[98:99], v2 offset:0x3400
	ds_read_b64_tr_b16 v[100:101], v2 offset:0x3c00
	s_waitcnt lgkmcnt(8)
	v_mfma_f32_32x32x16_f16 v[50:65], v[6:9], v[102:105], v[50:65]
	v_mfma_f32_32x32x16_f16 v[50:65], v[10:13], v[106:109], v[50:65]
	v_mfma_f32_32x32x16_f16 v[50:65], v[14:17], v[110:113], v[50:65]
	v_mfma_f32_32x32x16_f16 v[50:65], v[82:85], v[188:191], v[50:65]
	ds_read_b64_tr_b16 v[102:103], v2 offset:0x600
	ds_read_b64_tr_b16 v[104:105], v2 offset:0xe00
	ds_read_b64_tr_b16 v[106:107], v2 offset:0x1600
	ds_read_b64_tr_b16 v[108:109], v2 offset:0x1e00
	ds_read_b64_tr_b16 v[110:111], v2 offset:0x2600
	ds_read_b64_tr_b16 v[112:113], v2 offset:0x2e00
	ds_read_b64_tr_b16 v[188:189], v2 offset:0x3600
	ds_read_b64_tr_b16 v[190:191], v2 offset:0x3e00
	s_waitcnt lgkmcnt(8)
	v_mfma_f32_32x32x16_f16 v[34:49], v[6:9], v[86:89], v[34:49]
	v_mfma_f32_32x32x16_f16 v[34:49], v[10:13], v[90:93], v[34:49]
	v_mfma_f32_32x32x16_f16 v[34:49], v[14:17], v[94:97], v[34:49]
	v_mfma_f32_32x32x16_f16 v[34:49], v[82:85], v[98:101], v[34:49]
	s_waitcnt lgkmcnt(0)
	v_mfma_f32_32x32x16_f16 v[18:33], v[6:9], v[102:105], v[18:33]
	v_mov_b32_e32 v187, v194
	v_mfma_f32_32x32x16_f16 v[18:33], v[10:13], v[106:109], v[18:33]
	v_mfma_f32_32x32x16_f16 v[18:33], v[14:17], v[110:113], v[18:33]
	v_mfma_f32_32x32x16_f16 v[18:33], v[82:85], v[188:191], v[18:33]

; __device__ __forceinline__ void partialSM(f32x16& p0, f32x16& p1, float& m_reg, float& mn, float& alpha, const float sc, const float C2) {
;     ...
;     if (__builtin_expect(__all((pmax - m_reg) * sc <= 8.0f), 1)) { mn = m_reg; alpha = 1.f; }
;     else { mn = fmaxf(m_reg, pmax); alpha = __builtin_amdgcn_exp2f((m_reg - mn) * C2); m_reg = mn; }
.Ldsa_slow:
	v_max_f32_e32 v102, v186, v86
	v_sub_f32_e32 v86, v186, v102
	v_mul_f32_e32 v86, 0x3e0293ee, v86
	v_exp_f32_e32 v86, v86
	v_mov_b32_e32 v186, v102
	s_nop 0
	v_cmp_gt_f32_e32 vcc, 1.0, v86
	s_cbranch_vccz .Ldsa_fast
	s_and_saveexec_b64 s[8:9], s[0:1]
	ds_write_b32 v179, v86 offset:128
	s_or_b64 exec, exec, s[8:9]
	s_waitcnt lgkmcnt(0)
	ds_read_b128 v[104:107], v1 offset:224
	ds_read_b128 v[108:111], v1 offset:192
	ds_read_b128 v[190:193], v1 offset:160
	ds_read_b128 v[194:197], v1 offset:128
	s_waitcnt lgkmcnt(3)
	v_pk_mul_f32 v[80:81], v[80:81], v[106:107]
	s_waitcnt lgkmcnt(2)
	v_pk_mul_f32 v[76:77], v[76:77], v[110:111]
	s_waitcnt lgkmcnt(1)
	v_pk_mul_f32 v[72:73], v[72:73], v[192:193]
	s_waitcnt lgkmcnt(0)
	v_pk_mul_f32 v[68:69], v[68:69], v[196:197]
	v_pk_mul_f32 v[78:79], v[78:79], v[104:105]
	v_pk_mul_f32 v[74:75], v[74:75], v[108:109]
	v_pk_mul_f32 v[70:71], v[70:71], v[190:191]
	v_pk_mul_f32 v[66:67], v[66:67], v[194:195]
	v_pk_mul_f32 v[64:65], v[64:65], v[106:107]
	v_pk_mul_f32 v[60:61], v[60:61], v[110:111]
	v_pk_mul_f32 v[56:57], v[56:57], v[192:193]
	v_pk_mul_f32 v[52:53], v[52:53], v[196:197]
	v_pk_mul_f32 v[62:63], v[62:63], v[104:105]
	v_pk_mul_f32 v[58:59], v[58:59], v[108:109]
	v_pk_mul_f32 v[54:55], v[54:55], v[190:191]
	v_pk_mul_f32 v[50:51], v[50:51], v[194:195]
	v_pk_mul_f32 v[48:49], v[48:49], v[106:107]
	v_pk_mul_f32 v[44:45], v[44:45], v[110:111]
	v_pk_mul_f32 v[40:41], v[40:41], v[192:193]
	v_pk_mul_f32 v[36:37], v[36:37], v[196:197]
	v_pk_mul_f32 v[46:47], v[46:47], v[104:105]
	v_pk_mul_f32 v[42:43], v[42:43], v[108:109]
	v_pk_mul_f32 v[38:39], v[38:39], v[190:191]
	v_pk_mul_f32 v[34:35], v[34:35], v[194:195]
	v_pk_mul_f32 v[32:33], v[32:33], v[106:107]
	v_pk_mul_f32 v[28:29], v[28:29], v[110:111]
	v_pk_mul_f32 v[24:25], v[24:25], v[192:193]
	v_pk_mul_f32 v[20:21], v[20:21], v[196:197]
	v_pk_mul_f32 v[30:31], v[30:31], v[104:105]
	v_pk_mul_f32 v[26:27], v[26:27], v[108:109]
	v_pk_mul_f32 v[22:23], v[22:23], v[190:191]
	v_pk_mul_f32 v[18:19], v[18:19], v[194:195]
	s_branch .Ldsa_fast

; __device__ __forceinline__ float max3f(float a, float b, float c) { return __builtin_fmaxf(__builtin_fmaxf(a, b), c); }
; __device__ __forceinline__ void partialSM(f32x16& p0, f32x16& p1, float& m_reg, float& mn, float& alpha, const float sc, const float C2) {
;     float pmax = max3f(p0[0], p0[1], p0[2]);
; #pragma unroll
;     for (int r = 3; r < 15; r += 2) pmax = max3f(pmax, p0[r], p0[r + 1]);
;     pmax = max3f(pmax, p0[15], p1[0]);
; #pragma unroll
;     for (int r = 1; r < 15; r += 2) pmax = max3f(pmax, p1[r], p1[r + 1]);
;     pmax = fmaxf(pmax, p1[15]);
;     { auto rr = __builtin_amdgcn_permlane32_swap(__float_as_uint(pmax), __float_as_uint(pmax), false, false);
;       pmax = fmaxf(__uint_as_float(rr[0]), __uint_as_float(rr[1])); }
;     if (__builtin_expect(__all((pmax - m_reg) * sc <= 8.0f), 1)) { mn = m_reg; alpha = 1.f; }
;     else { mn = fmaxf(m_reg, pmax); alpha = __builtin_amdgcn_exp2f((m_reg - mn) * C2); m_reg = mn; }
.LBB0_4957:
	v_max_f32_e32 v4, v98, v99
	v_max3_f32 v4, v4, v100, v101
	v_max3_f32 v4, v4, v102, v103
	v_max3_f32 v4, v4, v104, v105
	v_max3_f32 v4, v4, v106, v107
	v_max3_f32 v4, v4, v108, v109
	v_max3_f32 v4, v4, v110, v111
	v_max3_f32 v4, v4, v112, v113
	v_max3_f32 v4, v4, v82, v83
	v_max3_f32 v4, v4, v84, v85
	v_max3_f32 v4, v4, v86, v87
	v_max3_f32 v4, v4, v88, v89
	v_max3_f32 v4, v4, v90, v91
	v_max3_f32 v4, v4, v92, v93
	v_max3_f32 v4, v4, v94, v95
	v_max3_f32 v4, v4, v96, v97
	v_mov_b32_e32 v5, v4
	s_nop 1
	v_permlane32_swap_b32_e32 v4, v5
	v_max_f32_e32 v4, v4, v5
	v_sub_f32_e32 v5, v4, v236
	v_mul_f32_e32 v5, 0x3db504f3, v5
	v_cmp_ge_f32_e32 vcc, s87, v5
	v_mov_b32_e32 v118, 1.0
	s_cmp_eq_u64 vcc, exec
	s_cbranch_scc0 .Lmoba_slow
; #define FA_SBAR() __builtin_amdgcn_sched_barrier(0)
; #define FA_RD8(S, d0) do { constexpr int b_ = v_rd_off(d0, 0, 0); FA_TRRD(S##l0, b_); FA_TRRD(S##h0, b_ + 2048); FA_TRRD(S##l1, b_ + 4096); FA_TRRD(S##h1, b_ + 6144); FA_TRRD(S##l2, b_ + 8192); FA_TRRD(S##h2, b_ + 10240); FA_TRRD(S##l3, b_ + 12288); FA_TRRD(S##h3, b_ + 14336); } while (0)
; __device__ __forceinline__ void partialSM(f32x16& p0, f32x16& p1, float& m_reg, float& mn, float& alpha, const float sc, const float C2) {
;     ...
;     const float mnL = -mn * C2;
; #pragma unroll
;     for (int r = 0; r < 16; ++r) p0[r] = __builtin_amdgcn_exp2f(fmaf(p0[r], C2, mnL));
; #pragma unroll
;     for (int r = 0; r < 16; ++r) p1[r] = __builtin_amdgcn_exp2f(fmaf(p1[r], C2, mnL));
; }
; __device__ __forceinline__ void finishSM(const f32x16& p0, const f32x16& p1, float alpha, float& l_reg, half8& pa0, half8& pa1, half8& pa2, half8& pa3) {
;     f32x2 s2 = {0.f, 0.f};
; #pragma unroll
;     for (int r = 0; r < 16; r += 2) { s2 += (f32x2){p0[r], p0[r + 1]}; s2 += (f32x2){p1[r], p1[r + 1]}; }
;     float ps = s2[0] + s2[1];
;     { auto rr = __builtin_amdgcn_permlane32_swap(__float_as_uint(ps), __float_as_uint(ps), false, false);
;       ps = __uint_as_float(rr[0]) + __uint_as_float(rr[1]); }
;     l_reg = l_reg * alpha + ps;
;     ...
;     FA_PK4(p0, 0, pa0); FA_PK4(p0, 8, pa1); FA_PK4(p1, 0, pa2); FA_PK4(p1, 8, pa3);
;     ...
; }
; __device__ __forceinline__ void pv_tile2(f32x16* o, int vb0, half8 pa0, half8 pa1, half8 pa2, half8 pa3) {
;     ...
;     s16x4 al0, al1, al2, al3, ah0, ah1, ah2, ah3, bl0, bl1, bl2, bl3, bh0, bh1, bh2, bh3;
;     FA_RD8(a, 0);
;     FA_RD8(b, 1); asm volatile("s_waitcnt lgkmcnt(8)" ::: "memory"); FA_SBAR(); FA_MM4(a, 0); FA_SBAR();
;     FA_RD8(a, 2); asm volatile("s_waitcnt lgkmcnt(8)" ::: "memory"); FA_SBAR(); FA_MM4(b, 1); FA_SBAR();
;     FA_RD8(b, 3); asm volatile("s_waitcnt lgkmcnt(8)" ::: "memory"); FA_SBAR(); FA_MM4(a, 2); FA_SBAR();
;     asm volatile("s_waitcnt lgkmcnt(0)" ::: "memory"); FA_SBAR(); FA_MM4(b, 3);
;     ...
; }
.Lmoba_fast:
.LBB0_4961:
	v_mul_f32_e32 v5, 0xbe0293ee, v236
	v_fmamk_f32 v6, v98, 0x3e0293ee, v5
	v_fmamk_f32 v7, v99, 0x3e0293ee, v5
	v_exp_f32_e32 v6, v6
	v_exp_f32_e32 v7, v7
	v_fmamk_f32 v82, v82, 0x3e0293ee, v5
	v_fmamk_f32 v83, v83, 0x3e0293ee, v5
	v_fmamk_f32 v8, v100, 0x3e0293ee, v5
	v_fmamk_f32 v9, v101, 0x3e0293ee, v5
	v_exp_f32_e32 v82, v82
	v_exp_f32_e32 v83, v83
	v_exp_f32_e32 v8, v8
	v_exp_f32_e32 v9, v9
	v_fmamk_f32 v84, v84, 0x3e0293ee, v5
	v_fmamk_f32 v85, v85, 0x3e0293ee, v5
	v_fmamk_f32 v10, v102, 0x3e0293ee, v5
	v_fmamk_f32 v11, v103, 0x3e0293ee, v5
	v_exp_f32_e32 v84, v84
	v_exp_f32_e32 v85, v85
	v_exp_f32_e32 v10, v10
	v_exp_f32_e32 v11, v11
	v_fmamk_f32 v86, v86, 0x3e0293ee, v5
	v_fmamk_f32 v87, v87, 0x3e0293ee, v5
	v_pk_add_f32 v[102:103], v[6:7], 0 op_sel_hi:[1,0]
	v_fmamk_f32 v12, v104, 0x3e0293ee, v5
	v_fmamk_f32 v13, v105, 0x3e0293ee, v5
	v_exp_f32_e32 v86, v86
	v_exp_f32_e32 v87, v87
	v_pk_add_f32 v[102:103], v[82:83], v[102:103]
	v_exp_f32_e32 v12, v12
	v_exp_f32_e32 v13, v13
	v_fmamk_f32 v88, v88, 0x3e0293ee, v5
	v_fmamk_f32 v89, v89, 0x3e0293ee, v5
	v_pk_add_f32 v[102:103], v[8:9], v[102:103]
	v_fmamk_f32 v14, v106, 0x3e0293ee, v5
	v_fmamk_f32 v15, v107, 0x3e0293ee, v5
	v_exp_f32_e32 v88, v88
	v_exp_f32_e32 v89, v89
	v_pk_add_f32 v[102:103], v[84:85], v[102:103]
	v_exp_f32_e32 v14, v14
	v_exp_f32_e32 v15, v15
	v_fmamk_f32 v90, v90, 0x3e0293ee, v5
	v_fmamk_f32 v91, v91, 0x3e0293ee, v5
	v_pk_add_f32 v[102:103], v[10:11], v[102:103]
	v_fmamk_f32 v16, v108, 0x3e0293ee, v5
	v_fmamk_f32 v17, v109, 0x3e0293ee, v5
	v_exp_f32_e32 v90, v90
	v_exp_f32_e32 v91, v91
	v_pk_add_f32 v[102:103], v[86:87], v[102:103]
	v_exp_f32_e32 v16, v16
	v_exp_f32_e32 v17, v17
	v_fmamk_f32 v92, v92, 0x3e0293ee, v5
	v_fmamk_f32 v93, v93, 0x3e0293ee, v5
	v_pk_add_f32 v[102:103], v[12:13], v[102:103]
	v_fmamk_f32 v98, v110, 0x3e0293ee, v5
	v_fmamk_f32 v99, v111, 0x3e0293ee, v5
	v_exp_f32_e32 v92, v92
	v_exp_f32_e32 v93, v93
	v_pk_add_f32 v[102:103], v[88:89], v[102:103]
	v_exp_f32_e32 v98, v98
	v_exp_f32_e32 v99, v99
	v_fmamk_f32 v94, v94, 0x3e0293ee, v5
	v_fmamk_f32 v95, v95, 0x3e0293ee, v5
	v_pk_add_f32 v[102:103], v[14:15], v[102:103]
	v_fmamk_f32 v100, v112, 0x3e0293ee, v5
	v_fmamk_f32 v101, v113, 0x3e0293ee, v5
	v_exp_f32_e32 v94, v94
	v_exp_f32_e32 v95, v95
	v_pk_add_f32 v[102:103], v[90:91], v[102:103]
	v_exp_f32_e32 v100, v100
	v_exp_f32_e32 v101, v101
	v_fmamk_f32 v96, v96, 0x3e0293ee, v5
	v_fmac_f32_e32 v5, 0x3e0293ee, v97
	v_pk_add_f32 v[102:103], v[16:17], v[102:103]
	v_exp_f32_e32 v96, v96
	v_exp_f32_e32 v97, v5
	v_pk_add_f32 v[102:103], v[92:93], v[102:103]
	v_cvt_pk_f16_f32 v4, v6, v7
	v_pk_add_f32 v[102:103], v[98:99], v[102:103]
	v_cvt_pk_f16_f32 v5, v8, v9
	v_pk_add_f32 v[102:103], v[94:95], v[102:103]
	v_cvt_pk_f16_f32 v6, v10, v11
	v_pk_add_f32 v[102:103], v[100:101], v[102:103]
	v_cvt_pk_f16_f32 v7, v12, v13
	v_pk_add_f32 v[102:103], v[96:97], v[102:103]
	v_cvt_pk_f16_f32 v8, v14, v15
	v_pk_add_f32 v[102:103], v[102:103], v[102:103] op_sel:[0,1] op_sel_hi:[1,0]
	v_cvt_pk_f16_f32 v9, v16, v17
	v_mov_b32_e32 v103, v102
	v_cvt_pk_f16_f32 v10, v98, v99
	v_cvt_pk_f16_f32 v11, v100, v101
	v_permlane32_swap_b32_e32 v102, v103
	v_cvt_pk_f16_f32 v12, v82, v83
	v_add_f32_e32 v103, v102, v103
	v_cvt_pk_f16_f32 v13, v84, v85
	v_fma_f32 v237, v237, v118, v103
	v_cvt_pk_f16_f32 v14, v86, v87
	v_cvt_pk_f16_f32 v15, v88, v89
	v_cvt_pk_f16_f32 v82, v90, v91
	v_cvt_pk_f16_f32 v83, v92, v93
	v_cvt_pk_f16_f32 v84, v94, v95
	v_cvt_pk_f16_f32 v85, v96, v97
	v_permlane32_swap_b32_e32 v4, v6
	v_permlane32_swap_b32_e32 v5, v7
	v_permlane32_swap_b32_e32 v8, v10
	v_permlane32_swap_b32_e32 v9, v11
	v_permlane32_swap_b32_e32 v12, v14
	v_permlane32_swap_b32_e32 v13, v15
	v_permlane32_swap_b32_e32 v82, v84
	v_permlane32_swap_b32_e32 v83, v85
	v_add_u32_e32 v2, v234, v2
	ds_read_b64_tr_b16 v[86:87], v2 offset:0
	ds_read_b64_tr_b16 v[88:89], v2 offset:0x800
	ds_read_b64_tr_b16 v[90:91], v2 offset:0x1000
	ds_read_b64_tr_b16 v[92:93], v2 offset:0x1800
	ds_read_b64_tr_b16 v[94:95], v2 offset:0x2000
	ds_read_b64_tr_b16 v[96:97], v2 offset:0x2800
	ds_read_b64_tr_b16 v[98:99], v2 offset:0x3000
	ds_read_b64_tr_b16 v[100:101], v2 offset:0x3800
	ds_read_b64_tr_b16 v[102:103], v2 offset:0x200
	ds_read_b64_tr_b16 v[104:105], v2 offset:0xa00
	ds_read_b64_tr_b16 v[106:107], v2 offset:0x1200
	ds_read_b64_tr_b16 v[108:109], v2 offset:0x1a00
	ds_read_b64_tr_b16 v[110:111], v2 offset:0x2200
	ds_read_b64_tr_b16 v[112:113], v2 offset:0x2a00
	ds_read_b64_tr_b16 v[114:115], v2 offset:0x3200
	ds_read_b64_tr_b16 v[116:117], v2 offset:0x3a00
	s_waitcnt lgkmcnt(8)
	s_nop 0
	v_mfma_f32_32x32x16_f16 v[66:81], v[4:7], v[86:89], v[66:81]
	v_mfma_f32_32x32x16_f16 v[66:81], v[8:11], v[90:93], v[66:81]
	v_mfma_f32_32x32x16_f16 v[66:81], v[12:15], v[94:97], v[66:81]
	v_mfma_f32_32x32x16_f16 v[66:81], v[82:85], v[98:101], v[66:81]
	ds_read_b64_tr_b16 v[86:87], v2 offset:0x400
	ds_read_b64_tr_b16 v[88:89], v2 offset:0xc00
	ds_read_b64_tr_b16 v[90:91], v2 offset:0x1400
	ds_read_b64_tr_b16 v[92:93], v2 offset:0x1c00
	ds_read_b64_tr_b16 v[94:95], v2 offset:0x2400
	ds_read_b64_tr_b16 v[96:97], v2 offset:0x2c00
	ds_read_b64_tr_b16 v[98:99], v2 offset:0x3400
	ds_read_b64_tr_b16 v[100:101], v2 offset:0x3c00
	s_waitcnt lgkmcnt(8)
	v_mfma_f32_32x32x16_f16 v[50:65], v[4:7], v[102:105], v[50:65]
	v_mfma_f32_32x32x16_f16 v[50:65], v[8:11], v[106:109], v[50:65]
	v_mfma_f32_32x32x16_f16 v[50:65], v[12:15], v[110:113], v[50:65]
	v_mfma_f32_32x32x16_f16 v[50:65], v[82:85], v[114:117], v[50:65]
	ds_read_b64_tr_b16 v[102:103], v2 offset:0x600
	ds_read_b64_tr_b16 v[104:105], v2 offset:0xe00
	ds_read_b64_tr_b16 v[106:107], v2 offset:0x1600
	ds_read_b64_tr_b16 v[108:109], v2 offset:0x1e00
	ds_read_b64_tr_b16 v[110:111], v2 offset:0x2600
	ds_read_b64_tr_b16 v[112:113], v2 offset:0x2e00
	ds_read_b64_tr_b16 v[114:115], v2 offset:0x3600
	ds_read_b64_tr_b16 v[116:117], v2 offset:0x3e00
	s_waitcnt lgkmcnt(8)
	v_mfma_f32_32x32x16_f16 v[34:49], v[4:7], v[86:89], v[34:49]
	v_mfma_f32_32x32x16_f16 v[34:49], v[8:11], v[90:93], v[34:49]
	v_mfma_f32_32x32x16_f16 v[34:49], v[12:15], v[94:97], v[34:49]
	v_mfma_f32_32x32x16_f16 v[34:49], v[82:85], v[98:101], v[34:49]
	s_waitcnt lgkmcnt(0)
	v_mfma_f32_32x32x16_f16 v[18:33], v[4:7], v[102:105], v[18:33]
	v_mfma_f32_32x32x16_f16 v[18:33], v[8:11], v[106:109], v[18:33]
	v_mfma_f32_32x32x16_f16 v[18:33], v[12:15], v[110:113], v[18:33]
	v_mfma_f32_32x32x16_f16 v[18:33], v[82:85], v[114:117], v[18:33]

; __device__ __forceinline__ void partialSM(f32x16& p0, f32x16& p1, float& m_reg, float& mn, float& alpha, const float sc, const float C2) {
;     ...
;     if (__builtin_expect(__all((pmax - m_reg) * sc <= 8.0f), 1)) { mn = m_reg; alpha = 1.f; }
;     else { mn = fmaxf(m_reg, pmax); alpha = __builtin_amdgcn_exp2f((m_reg - mn) * C2); m_reg = mn; }
.Lmoba_slow:
	v_max_f32_e32 v5, v236, v4
	v_sub_f32_e32 v4, v236, v5
	v_mul_f32_e32 v4, 0x3e0293ee, v4
	v_exp_f32_e32 v4, v4
	v_mov_b32_e32 v236, v5
	v_mov_b32_e32 v118, v4
	v_cmp_gt_f32_e32 vcc, 1.0, v4
	s_cbranch_vccz .Lmoba_fast
	s_and_saveexec_b64 s[8:9], s[0:1]
	ds_write_b32 v226, v4 offset:128
	s_or_b64 exec, exec, s[8:9]
	s_waitcnt lgkmcnt(0)
	ds_read_b128 v[6:9], v1 offset:224
	ds_read_b128 v[10:13], v1 offset:192
	ds_read_b128 v[14:17], v1 offset:160
	ds_read_b128 v[114:117], v1 offset:128
	s_waitcnt lgkmcnt(3)
	v_pk_mul_f32 v[80:81], v[80:81], v[8:9]
	s_waitcnt lgkmcnt(2)
	v_pk_mul_f32 v[76:77], v[76:77], v[12:13]
	s_waitcnt lgkmcnt(1)
	v_pk_mul_f32 v[72:73], v[72:73], v[16:17]
	s_waitcnt lgkmcnt(0)
	v_pk_mul_f32 v[68:69], v[68:69], v[116:117]
	v_pk_mul_f32 v[78:79], v[78:79], v[6:7]
	v_pk_mul_f32 v[74:75], v[74:75], v[10:11]
	v_pk_mul_f32 v[70:71], v[70:71], v[14:15]
	v_pk_mul_f32 v[66:67], v[66:67], v[114:115]
	v_pk_mul_f32 v[64:65], v[64:65], v[8:9]
	v_pk_mul_f32 v[60:61], v[60:61], v[12:13]
	v_pk_mul_f32 v[56:57], v[56:57], v[16:17]
	v_pk_mul_f32 v[52:53], v[52:53], v[116:117]
	v_pk_mul_f32 v[62:63], v[62:63], v[6:7]
	v_pk_mul_f32 v[58:59], v[58:59], v[10:11]
	v_pk_mul_f32 v[54:55], v[54:55], v[14:15]
	v_pk_mul_f32 v[50:51], v[50:51], v[114:115]
	v_pk_mul_f32 v[48:49], v[48:49], v[8:9]
	v_pk_mul_f32 v[44:45], v[44:45], v[12:13]
	v_pk_mul_f32 v[40:41], v[40:41], v[16:17]
	v_pk_mul_f32 v[36:37], v[36:37], v[116:117]
	v_pk_mul_f32 v[46:47], v[46:47], v[6:7]
	v_pk_mul_f32 v[42:43], v[42:43], v[10:11]
	v_pk_mul_f32 v[38:39], v[38:39], v[14:15]
	v_pk_mul_f32 v[34:35], v[34:35], v[114:115]
	v_pk_mul_f32 v[32:33], v[32:33], v[8:9]
	v_pk_mul_f32 v[28:29], v[28:29], v[12:13]
	v_pk_mul_f32 v[24:25], v[24:25], v[16:17]
	v_pk_mul_f32 v[20:21], v[20:21], v[116:117]
	v_pk_mul_f32 v[30:31], v[30:31], v[6:7]
	v_pk_mul_f32 v[26:27], v[26:27], v[10:11]
	v_pk_mul_f32 v[22:23], v[22:23], v[14:15]
	v_pk_mul_f32 v[18:19], v[18:19], v[114:115]
	s_branch .Lmoba_fast

; __device__ __forceinline__ float max3f(float a, float b, float c) { return __builtin_fmaxf(__builtin_fmaxf(a, b), c); }
; __device__ __forceinline__ void partialSM(f32x16& p0, f32x16& p1, float& m_reg, float& mn, float& alpha, const float sc, const float C2) {
;     float pmax = max3f(p0[0], p0[1], p0[2]);
; #pragma unroll
;     for (int r = 3; r < 15; r += 2) pmax = max3f(pmax, p0[r], p0[r + 1]);
;     pmax = max3f(pmax, p0[15], p1[0]);
; #pragma unroll
;     for (int r = 1; r < 15; r += 2) pmax = max3f(pmax, p1[r], p1[r + 1]);
;     pmax = fmaxf(pmax, p1[15]);
;     { auto rr = __builtin_amdgcn_permlane32_swap(__float_as_uint(pmax), __float_as_uint(pmax), false, false);
;       pmax = fmaxf(__uint_as_float(rr[0]), __uint_as_float(rr[1])); }
;     if (__builtin_expect(__all((pmax - m_reg) * sc <= 8.0f), 1)) { mn = m_reg; alpha = 1.f; }
;     else { mn = fmaxf(m_reg, pmax); alpha = __builtin_amdgcn_exp2f((m_reg - mn) * C2); m_reg = mn; }
.LBB0_4977:
	s_nop 8
	v_max_f32_e32 v4, v98, v99
	v_max3_f32 v4, v4, v100, v101
	v_max3_f32 v4, v4, v102, v103
	v_max3_f32 v4, v4, v104, v105
	v_max3_f32 v4, v4, v106, v107
	v_max3_f32 v4, v4, v108, v109
	v_max3_f32 v4, v4, v110, v111
	v_max3_f32 v4, v4, v112, v113
	v_max3_f32 v4, v4, v82, v83
	v_max3_f32 v4, v4, v84, v85
	v_max3_f32 v4, v4, v86, v87
	v_max3_f32 v4, v4, v88, v89
	v_max3_f32 v4, v4, v90, v91
	v_max3_f32 v4, v4, v92, v93
	v_max3_f32 v4, v4, v94, v95
	v_max3_f32 v4, v4, v96, v97
	v_mov_b32_e32 v5, v4
	s_nop 1
	v_permlane32_swap_b32_e32 v4, v5
	v_max_f32_e32 v4, v4, v5
	v_sub_f32_e32 v5, v4, v228
	v_mul_f32_e32 v5, 0x3d93cd3a, v5
	v_cmp_ge_f32_e32 vcc, s87, v5
	v_mov_b32_e32 v214, 1.0
	s_cmp_eq_u64 vcc, exec
	s_cbranch_scc0 .Lmla_slow
; #define FA_SBAR() __builtin_amdgcn_sched_barrier(0)
; #define FA_RD8(S, d0) do { constexpr int b_ = v_rd_off(d0, 0, 0); FA_TRRD(S##l0, b_); FA_TRRD(S##h0, b_ + 2048); FA_TRRD(S##l1, b_ + 4096); FA_TRRD(S##h1, b_ + 6144); FA_TRRD(S##l2, b_ + 8192); FA_TRRD(S##h2, b_ + 10240); FA_TRRD(S##l3, b_ + 12288); FA_TRRD(S##h3, b_ + 14336); } while (0)
; __device__ __forceinline__ void partialSM(f32x16& p0, f32x16& p1, float& m_reg, float& mn, float& alpha, const float sc, const float C2) {
;     ...
;     const float mnL = -mn * C2;
; #pragma unroll
;     for (int r = 0; r < 16; ++r) p0[r] = __builtin_amdgcn_exp2f(fmaf(p0[r], C2, mnL));
; #pragma unroll
;     for (int r = 0; r < 16; ++r) p1[r] = __builtin_amdgcn_exp2f(fmaf(p1[r], C2, mnL));
; }
; __device__ __forceinline__ void finishSM(const f32x16& p0, const f32x16& p1, float alpha, float& l_reg, half8& pa0, half8& pa1, half8& pa2, half8& pa3) {
;     f32x2 s2 = {0.f, 0.f};
; #pragma unroll
;     for (int r = 0; r < 16; r += 2) { s2 += (f32x2){p0[r], p0[r + 1]}; s2 += (f32x2){p1[r], p1[r + 1]}; }
;     float ps = s2[0] + s2[1];
;     { auto rr = __builtin_amdgcn_permlane32_swap(__float_as_uint(ps), __float_as_uint(ps), false, false);
;       ps = __uint_as_float(rr[0]) + __uint_as_float(rr[1]); }
;     l_reg = l_reg * alpha + ps;
;     ...
;     FA_PK4(p0, 0, pa0); FA_PK4(p0, 8, pa1); FA_PK4(p1, 0, pa2); FA_PK4(p1, 8, pa3);
;     ...
; }
; __device__ __forceinline__ void pv_tile2(f32x16* o, int vb0, half8 pa0, half8 pa1, half8 pa2, half8 pa3) {
;     ...
;     s16x4 al0, al1, al2, al3, ah0, ah1, ah2, ah3, bl0, bl1, bl2, bl3, bh0, bh1, bh2, bh3;
;     FA_RD8(a, 0);
;     FA_RD8(b, 1); asm volatile("s_waitcnt lgkmcnt(8)" ::: "memory"); FA_SBAR(); FA_MM4(a, 0); FA_SBAR();
;     FA_RD8(a, 2); asm volatile("s_waitcnt lgkmcnt(8)" ::: "memory"); FA_SBAR(); FA_MM4(b, 1); FA_SBAR();
;     FA_RD8(b, 3); asm volatile("s_waitcnt lgkmcnt(8)" ::: "memory"); FA_SBAR(); FA_MM4(a, 2); FA_SBAR();
;     asm volatile("s_waitcnt lgkmcnt(0)" ::: "memory"); FA_SBAR(); FA_MM4(b, 3);
;     ...
; }
.Lmla_fast:
.LBB0_4981:
	v_mul_f32_e32 v5, 0xbdd53b94, v228
	v_fmamk_f32 v6, v98, 0x3dd53b94, v5
	v_fmamk_f32 v7, v99, 0x3dd53b94, v5
	v_exp_f32_e32 v6, v6
	v_exp_f32_e32 v7, v7
	v_fmamk_f32 v82, v82, 0x3dd53b94, v5
	v_fmamk_f32 v83, v83, 0x3dd53b94, v5
	v_fmamk_f32 v8, v100, 0x3dd53b94, v5
	v_fmamk_f32 v9, v101, 0x3dd53b94, v5
	v_exp_f32_e32 v82, v82
	v_exp_f32_e32 v83, v83
	v_exp_f32_e32 v8, v8
	v_exp_f32_e32 v9, v9
	v_fmamk_f32 v84, v84, 0x3dd53b94, v5
	v_fmamk_f32 v85, v85, 0x3dd53b94, v5
	v_fmamk_f32 v10, v102, 0x3dd53b94, v5
	v_fmamk_f32 v11, v103, 0x3dd53b94, v5
	v_exp_f32_e32 v84, v84
	v_exp_f32_e32 v85, v85
	v_exp_f32_e32 v10, v10
	v_exp_f32_e32 v11, v11
	v_fmamk_f32 v86, v86, 0x3dd53b94, v5
	v_fmamk_f32 v87, v87, 0x3dd53b94, v5
	v_pk_add_f32 v[102:103], v[6:7], 0 op_sel_hi:[1,0]
	v_fmamk_f32 v12, v104, 0x3dd53b94, v5
	v_fmamk_f32 v13, v105, 0x3dd53b94, v5
	v_exp_f32_e32 v86, v86
	v_exp_f32_e32 v87, v87
	v_pk_add_f32 v[102:103], v[82:83], v[102:103]
	v_exp_f32_e32 v12, v12
	v_exp_f32_e32 v13, v13
	v_fmamk_f32 v88, v88, 0x3dd53b94, v5
	v_fmamk_f32 v89, v89, 0x3dd53b94, v5
	v_pk_add_f32 v[102:103], v[8:9], v[102:103]
	v_fmamk_f32 v14, v106, 0x3dd53b94, v5
	v_fmamk_f32 v15, v107, 0x3dd53b94, v5
	v_exp_f32_e32 v88, v88
	v_exp_f32_e32 v89, v89
	v_pk_add_f32 v[102:103], v[84:85], v[102:103]
	v_exp_f32_e32 v14, v14
	v_exp_f32_e32 v15, v15
	v_fmamk_f32 v90, v90, 0x3dd53b94, v5
	v_fmamk_f32 v91, v91, 0x3dd53b94, v5
	v_pk_add_f32 v[102:103], v[10:11], v[102:103]
	v_fmamk_f32 v16, v108, 0x3dd53b94, v5
	v_fmamk_f32 v17, v109, 0x3dd53b94, v5
	v_exp_f32_e32 v90, v90
	v_exp_f32_e32 v91, v91
	v_pk_add_f32 v[102:103], v[86:87], v[102:103]
	v_exp_f32_e32 v16, v16
	v_exp_f32_e32 v17, v17
	v_fmamk_f32 v92, v92, 0x3dd53b94, v5
	v_fmamk_f32 v93, v93, 0x3dd53b94, v5
	v_pk_add_f32 v[102:103], v[12:13], v[102:103]
	v_fmamk_f32 v98, v110, 0x3dd53b94, v5
	v_fmamk_f32 v99, v111, 0x3dd53b94, v5
	v_exp_f32_e32 v92, v92
	v_exp_f32_e32 v93, v93
	v_pk_add_f32 v[102:103], v[88:89], v[102:103]
	v_exp_f32_e32 v98, v98
	v_exp_f32_e32 v99, v99
	v_fmamk_f32 v94, v94, 0x3dd53b94, v5
	v_fmamk_f32 v95, v95, 0x3dd53b94, v5
	v_pk_add_f32 v[102:103], v[14:15], v[102:103]
	v_fmamk_f32 v100, v112, 0x3dd53b94, v5
	v_fmamk_f32 v101, v113, 0x3dd53b94, v5
	v_exp_f32_e32 v94, v94
	v_exp_f32_e32 v95, v95
	v_pk_add_f32 v[102:103], v[90:91], v[102:103]
	v_exp_f32_e32 v100, v100
	v_exp_f32_e32 v101, v101
	v_fmamk_f32 v96, v96, 0x3dd53b94, v5
	v_fmac_f32_e32 v5, 0x3dd53b94, v97
	v_pk_add_f32 v[102:103], v[16:17], v[102:103]
	v_exp_f32_e32 v96, v96
	v_exp_f32_e32 v97, v5
	v_pk_add_f32 v[102:103], v[92:93], v[102:103]
	v_cvt_pk_f16_f32 v4, v6, v7
	v_pk_add_f32 v[102:103], v[98:99], v[102:103]
	v_cvt_pk_f16_f32 v5, v8, v9
	v_pk_add_f32 v[102:103], v[94:95], v[102:103]
	v_cvt_pk_f16_f32 v6, v10, v11
	v_pk_add_f32 v[102:103], v[100:101], v[102:103]
	v_cvt_pk_f16_f32 v7, v12, v13
	v_pk_add_f32 v[102:103], v[96:97], v[102:103]
	v_cvt_pk_f16_f32 v8, v14, v15
	v_pk_add_f32 v[102:103], v[102:103], v[102:103] op_sel:[0,1] op_sel_hi:[1,0]
	v_cvt_pk_f16_f32 v9, v16, v17
	v_mov_b32_e32 v103, v102
	v_cvt_pk_f16_f32 v10, v98, v99
	v_cvt_pk_f16_f32 v11, v100, v101
	v_permlane32_swap_b32_e32 v102, v103
	v_cvt_pk_f16_f32 v12, v82, v83
	v_add_f32_e32 v103, v102, v103
	v_cvt_pk_f16_f32 v13, v84, v85
	v_fma_f32 v229, v229, v214, v103
	v_cvt_pk_f16_f32 v14, v86, v87
	v_cvt_pk_f16_f32 v15, v88, v89
	v_cvt_pk_f16_f32 v82, v90, v91
	v_cvt_pk_f16_f32 v83, v92, v93
	v_cvt_pk_f16_f32 v84, v94, v95
	v_cvt_pk_f16_f32 v85, v96, v97
	v_permlane32_swap_b32_e32 v4, v6
	v_permlane32_swap_b32_e32 v5, v7
	v_permlane32_swap_b32_e32 v8, v10
	v_permlane32_swap_b32_e32 v9, v11
	v_permlane32_swap_b32_e32 v12, v14
	v_permlane32_swap_b32_e32 v13, v15
	v_permlane32_swap_b32_e32 v82, v84
	v_permlane32_swap_b32_e32 v83, v85
	v_add_u32_e32 v2, v225, v2
	ds_read_b64_tr_b16 v[86:87], v2 offset:0
	ds_read_b64_tr_b16 v[88:89], v2 offset:0x800
	ds_read_b64_tr_b16 v[90:91], v2 offset:0x1000
	ds_read_b64_tr_b16 v[92:93], v2 offset:0x1800
	ds_read_b64_tr_b16 v[94:95], v2 offset:0x2000
	ds_read_b64_tr_b16 v[96:97], v2 offset:0x2800
	ds_read_b64_tr_b16 v[98:99], v2 offset:0x3000
	ds_read_b64_tr_b16 v[100:101], v2 offset:0x3800
	ds_read_b64_tr_b16 v[102:103], v2 offset:0x200
	ds_read_b64_tr_b16 v[104:105], v2 offset:0xa00
	ds_read_b64_tr_b16 v[106:107], v2 offset:0x1200
	ds_read_b64_tr_b16 v[108:109], v2 offset:0x1a00
	ds_read_b64_tr_b16 v[110:111], v2 offset:0x2200
	ds_read_b64_tr_b16 v[112:113], v2 offset:0x2a00
	ds_read_b64_tr_b16 v[194:195], v2 offset:0x3200
	ds_read_b64_tr_b16 v[196:197], v2 offset:0x3a00
	s_waitcnt lgkmcnt(8)
	s_nop 0
	v_mfma_f32_32x32x16_f16 v[66:81], v[4:7], v[86:89], v[66:81]
	v_mfma_f32_32x32x16_f16 v[66:81], v[8:11], v[90:93], v[66:81]
	v_mfma_f32_32x32x16_f16 v[66:81], v[12:15], v[94:97], v[66:81]
	v_mfma_f32_32x32x16_f16 v[66:81], v[82:85], v[98:101], v[66:81]
	ds_read_b64_tr_b16 v[86:87], v2 offset:0x400
	ds_read_b64_tr_b16 v[88:89], v2 offset:0xc00
	ds_read_b64_tr_b16 v[90:91], v2 offset:0x1400
	ds_read_b64_tr_b16 v[92:93], v2 offset:0x1c00
	ds_read_b64_tr_b16 v[94:95], v2 offset:0x2400
	ds_read_b64_tr_b16 v[96:97], v2 offset:0x2c00
	ds_read_b64_tr_b16 v[98:99], v2 offset:0x3400
	ds_read_b64_tr_b16 v[100:101], v2 offset:0x3c00
	s_waitcnt lgkmcnt(8)
	v_mfma_f32_32x32x16_f16 v[50:65], v[4:7], v[102:105], v[50:65]
	v_mfma_f32_32x32x16_f16 v[50:65], v[8:11], v[106:109], v[50:65]
	v_mfma_f32_32x32x16_f16 v[50:65], v[12:15], v[110:113], v[50:65]
	v_mfma_f32_32x32x16_f16 v[50:65], v[82:85], v[194:197], v[50:65]
	ds_read_b64_tr_b16 v[102:103], v2 offset:0x600
	ds_read_b64_tr_b16 v[104:105], v2 offset:0xe00
	ds_read_b64_tr_b16 v[106:107], v2 offset:0x1600
	ds_read_b64_tr_b16 v[108:109], v2 offset:0x1e00
	ds_read_b64_tr_b16 v[110:111], v2 offset:0x2600
	ds_read_b64_tr_b16 v[112:113], v2 offset:0x2e00
	ds_read_b64_tr_b16 v[194:195], v2 offset:0x3600
	ds_read_b64_tr_b16 v[196:197], v2 offset:0x3e00
	s_waitcnt lgkmcnt(8)
	v_mfma_f32_32x32x16_f16 v[34:49], v[4:7], v[86:89], v[34:49]
	v_mfma_f32_32x32x16_f16 v[34:49], v[8:11], v[90:93], v[34:49]
	v_mfma_f32_32x32x16_f16 v[34:49], v[12:15], v[94:97], v[34:49]
	v_mfma_f32_32x32x16_f16 v[34:49], v[82:85], v[98:101], v[34:49]
	s_waitcnt lgkmcnt(0)
	v_mfma_f32_32x32x16_f16 v[18:33], v[4:7], v[102:105], v[18:33]
	v_mfma_f32_32x32x16_f16 v[18:33], v[8:11], v[106:109], v[18:33]
	v_mfma_f32_32x32x16_f16 v[18:33], v[12:15], v[110:113], v[18:33]
	v_mfma_f32_32x32x16_f16 v[18:33], v[82:85], v[194:197], v[18:33]

; __device__ __forceinline__ void partialSM(f32x16& p0, f32x16& p1, float& m_reg, float& mn, float& alpha, const float sc, const float C2) {
;     ...
;     if (__builtin_expect(__all((pmax - m_reg) * sc <= 8.0f), 1)) { mn = m_reg; alpha = 1.f; }
;     else { mn = fmaxf(m_reg, pmax); alpha = __builtin_amdgcn_exp2f((m_reg - mn) * C2); m_reg = mn; }
.Lmla_slow:
	v_max_f32_e32 v5, v228, v4
	v_sub_f32_e32 v4, v228, v5
	v_mul_f32_e32 v4, 0x3dd53b94, v4
	v_exp_f32_e32 v4, v4
	v_mov_b32_e32 v228, v5
	v_mov_b32_e32 v214, v4
	v_cmp_gt_f32_e32 vcc, 1.0, v4
	s_cbranch_vccz .Lmla_fast
	s_and_saveexec_b64 s[8:9], s[0:1]
	ds_write_b32 v206, v4 offset:128
	s_or_b64 exec, exec, s[8:9]
	s_waitcnt lgkmcnt(0)
	ds_read_b128 v[6:9], v1 offset:224
	ds_read_b128 v[10:13], v1 offset:192
	ds_read_b128 v[14:17], v1 offset:160
	ds_read_b128 v[194:197], v1 offset:128
	s_waitcnt lgkmcnt(3)
	v_pk_mul_f32 v[80:81], v[80:81], v[8:9]
	s_waitcnt lgkmcnt(2)
	v_pk_mul_f32 v[76:77], v[76:77], v[12:13]
	s_waitcnt lgkmcnt(1)
	v_pk_mul_f32 v[72:73], v[72:73], v[16:17]
	s_waitcnt lgkmcnt(0)
	v_pk_mul_f32 v[68:69], v[68:69], v[196:197]
	v_pk_mul_f32 v[78:79], v[78:79], v[6:7]
	v_pk_mul_f32 v[74:75], v[74:75], v[10:11]
	v_pk_mul_f32 v[70:71], v[70:71], v[14:15]
	v_pk_mul_f32 v[66:67], v[66:67], v[194:195]
	v_pk_mul_f32 v[64:65], v[64:65], v[8:9]
	v_pk_mul_f32 v[60:61], v[60:61], v[12:13]
	v_pk_mul_f32 v[56:57], v[56:57], v[16:17]
	v_pk_mul_f32 v[52:53], v[52:53], v[196:197]
	v_pk_mul_f32 v[62:63], v[62:63], v[6:7]
	v_pk_mul_f32 v[58:59], v[58:59], v[10:11]
	v_pk_mul_f32 v[54:55], v[54:55], v[14:15]
	v_pk_mul_f32 v[50:51], v[50:51], v[194:195]
	v_pk_mul_f32 v[48:49], v[48:49], v[8:9]
	v_pk_mul_f32 v[44:45], v[44:45], v[12:13]
	v_pk_mul_f32 v[40:41], v[40:41], v[16:17]
	v_pk_mul_f32 v[36:37], v[36:37], v[196:197]
	v_pk_mul_f32 v[46:47], v[46:47], v[6:7]
	v_pk_mul_f32 v[42:43], v[42:43], v[10:11]
	v_pk_mul_f32 v[38:39], v[38:39], v[14:15]
	v_pk_mul_f32 v[34:35], v[34:35], v[194:195]
	v_pk_mul_f32 v[32:33], v[32:33], v[8:9]
	v_pk_mul_f32 v[28:29], v[28:29], v[12:13]
	v_pk_mul_f32 v[24:25], v[24:25], v[16:17]
	v_pk_mul_f32 v[20:21], v[20:21], v[196:197]
	v_pk_mul_f32 v[30:31], v[30:31], v[6:7]
	v_pk_mul_f32 v[26:27], v[26:27], v[10:11]
	v_pk_mul_f32 v[22:23], v[22:23], v[14:15]
	v_pk_mul_f32 v[18:19], v[18:19], v[194:195]
	s_branch .Lmla_fast

; __device__ __forceinline__ float max3f(float a, float b, float c) { return __builtin_fmaxf(__builtin_fmaxf(a, b), c); }
; __device__ __forceinline__ void partialSM(f32x16& p0, f32x16& p1, float& m_reg, float& mn, float& alpha, const float sc, const float C2) {
;     float pmax = max3f(p0[0], p0[1], p0[2]);
; #pragma unroll
;     for (int r = 3; r < 15; r += 2) pmax = max3f(pmax, p0[r], p0[r + 1]);
;     pmax = max3f(pmax, p0[15], p1[0]);
; #pragma unroll
;     for (int r = 1; r < 15; r += 2) pmax = max3f(pmax, p1[r], p1[r + 1]);
;     pmax = fmaxf(pmax, p1[15]);
;     { auto rr = __builtin_amdgcn_permlane32_swap(__float_as_uint(pmax), __float_as_uint(pmax), false, false);
;       pmax = fmaxf(__uint_as_float(rr[0]), __uint_as_float(rr[1])); }
;     if (__builtin_expect(__all((pmax - m_reg) * sc <= 8.0f), 1)) { mn = m_reg; alpha = 1.f; }
;     else { mn = fmaxf(m_reg, pmax); alpha = __builtin_amdgcn_exp2f((m_reg - mn) * C2); m_reg = mn; }
.LBB0_4995:
	v_max_f32_e32 v91, v204, v204
	v_max_f32_e32 v92, v193, v193
	v_max_f32_e32 v91, v92, v91
	v_max3_f32 v91, v91, v191, v192
	v_max3_f32 v91, v91, v101, v102
	v_max3_f32 v91, v91, v99, v100
	v_max3_f32 v91, v91, v98, v90
	v_max3_f32 v91, v91, v88, v89
	v_max3_f32 v91, v91, v86, v87
	v_max3_f32 v91, v91, v84, v85
	v_max3_f32 v91, v91, v82, v83
	v_max3_f32 v91, v91, v16, v17
	v_max3_f32 v91, v91, v14, v15
	v_max3_f32 v91, v91, v12, v13
	v_max3_f32 v91, v91, v10, v11
	v_max3_f32 v91, v91, v8, v9
	v_max3_f32 v91, v91, v6, v7
	v_max3_f32 v91, v91, v4, v5
	v_mov_b32_e32 v92, v91
	s_nop 1
	v_permlane32_swap_b32_e32 v91, v92
	v_max_f32_e32 v91, v91, v92
	v_sub_f32_e32 v92, v91, v189
	v_mul_f32_e32 v92, 0x3db504f3, v92
	v_cmp_ge_f32_e32 vcc, s87, v92
	s_cmp_eq_u64 vcc, exec
	s_cbranch_scc0 .Lslc_slow
	v_mov_b32_e32 v91, 1.0
; #define FA_SBAR() __builtin_amdgcn_sched_barrier(0)
; #define FA_RD8(S, d0) do { constexpr int b_ = v_rd_off(d0, 0, 0); FA_TRRD(S##l0, b_); FA_TRRD(S##h0, b_ + 2048); FA_TRRD(S##l1, b_ + 4096); FA_TRRD(S##h1, b_ + 6144); FA_TRRD(S##l2, b_ + 8192); FA_TRRD(S##h2, b_ + 10240); FA_TRRD(S##l3, b_ + 12288); FA_TRRD(S##h3, b_ + 14336); } while (0)
; __device__ __forceinline__ void partialSM(f32x16& p0, f32x16& p1, float& m_reg, float& mn, float& alpha, const float sc, const float C2) {
;     ...
;     const float mnL = -mn * C2;
; #pragma unroll
;     for (int r = 0; r < 16; ++r) p0[r] = __builtin_amdgcn_exp2f(fmaf(p0[r], C2, mnL));
; #pragma unroll
;     for (int r = 0; r < 16; ++r) p1[r] = __builtin_amdgcn_exp2f(fmaf(p1[r], C2, mnL));
; }
; __device__ __forceinline__ void finishSM(const f32x16& p0, const f32x16& p1, float alpha, float& l_reg, half8& pa0, half8& pa1, half8& pa2, half8& pa3) {
;     f32x2 s2 = {0.f, 0.f};
; #pragma unroll
;     for (int r = 0; r < 16; r += 2) { s2 += (f32x2){p0[r], p0[r + 1]}; s2 += (f32x2){p1[r], p1[r + 1]}; }
;     float ps = s2[0] + s2[1];
;     { auto rr = __builtin_amdgcn_permlane32_swap(__float_as_uint(ps), __float_as_uint(ps), false, false);
;       ps = __uint_as_float(rr[0]) + __uint_as_float(rr[1]); }
;     l_reg = l_reg * alpha + ps;
;     ...
;     FA_PK4(p0, 0, pa0); FA_PK4(p0, 8, pa1); FA_PK4(p1, 0, pa2); FA_PK4(p1, 8, pa3);
;     ...
; }
; __device__ __forceinline__ void pv_tile2(f32x16* o, int vb0, half8 pa0, half8 pa1, half8 pa2, half8 pa3) {
;     ...
;     s16x4 al0, al1, al2, al3, ah0, ah1, ah2, ah3, bl0, bl1, bl2, bl3, bh0, bh1, bh2, bh3;
;     FA_RD8(a, 0);
;     FA_RD8(b, 1); asm volatile("s_waitcnt lgkmcnt(8)" ::: "memory"); FA_SBAR(); FA_MM4(a, 0); FA_SBAR();
;     FA_RD8(a, 2); asm volatile("s_waitcnt lgkmcnt(8)" ::: "memory"); FA_SBAR(); FA_MM4(b, 1); FA_SBAR();
;     FA_RD8(b, 3); asm volatile("s_waitcnt lgkmcnt(8)" ::: "memory"); FA_SBAR(); FA_MM4(a, 2); FA_SBAR();
;     asm volatile("s_waitcnt lgkmcnt(0)" ::: "memory"); FA_SBAR(); FA_MM4(b, 3);
;     ...
; }
.Lslc_fast:
.LBB0_4999:
	v_mul_f32_e32 v111, 0xbe0293ee, v189
	v_fmamk_f32 v92, v193, 0x3e0293ee, v111
	v_fmamk_f32 v93, v204, 0x3e0293ee, v111
	v_exp_f32_e32 v92, v92
	v_exp_f32_e32 v93, v93
	v_fmamk_f32 v82, v82, 0x3e0293ee, v111
	v_fmamk_f32 v83, v83, 0x3e0293ee, v111
	v_fmamk_f32 v94, v191, 0x3e0293ee, v111
	v_fmamk_f32 v95, v192, 0x3e0293ee, v111
	v_exp_f32_e32 v82, v82
	v_exp_f32_e32 v83, v83
	v_exp_f32_e32 v94, v94
	v_exp_f32_e32 v95, v95
	v_fmamk_f32 v16, v16, 0x3e0293ee, v111
	v_fmamk_f32 v17, v17, 0x3e0293ee, v111
	v_fmamk_f32 v96, v101, 0x3e0293ee, v111
	v_fmamk_f32 v97, v102, 0x3e0293ee, v111
	v_fmamk_f32 v99, v99, 0x3e0293ee, v111
	v_exp_f32_e32 v16, v16
	v_exp_f32_e32 v17, v17
	v_fmamk_f32 v12, v12, 0x3e0293ee, v111
	v_fmamk_f32 v10, v10, 0x3e0293ee, v111
	v_fmamk_f32 v8, v8, 0x3e0293ee, v111
	v_fmamk_f32 v6, v6, 0x3e0293ee, v111
	v_fmamk_f32 v4, v4, 0x3e0293ee, v111
	v_exp_f32_e32 v96, v96
	v_exp_f32_e32 v97, v97
	v_exp_f32_e32 v102, v99
	v_fmamk_f32 v99, v100, 0x3e0293ee, v111
	v_fmamk_f32 v98, v98, 0x3e0293ee, v111
	v_fmamk_f32 v90, v90, 0x3e0293ee, v111
	v_fmamk_f32 v88, v88, 0x3e0293ee, v111
	v_fmamk_f32 v89, v89, 0x3e0293ee, v111
	v_fmamk_f32 v86, v86, 0x3e0293ee, v111
	v_fmamk_f32 v87, v87, 0x3e0293ee, v111
	v_fmamk_f32 v84, v84, 0x3e0293ee, v111
	v_fmamk_f32 v85, v85, 0x3e0293ee, v111
	v_fmamk_f32 v14, v14, 0x3e0293ee, v111
	v_fmamk_f32 v15, v15, 0x3e0293ee, v111
	v_exp_f32_e32 v100, v12
	v_fmamk_f32 v12, v13, 0x3e0293ee, v111
	v_exp_f32_e32 v104, v10
	v_fmamk_f32 v10, v11, 0x3e0293ee, v111
	v_exp_f32_e32 v106, v8
	v_fmamk_f32 v8, v9, 0x3e0293ee, v111
	v_exp_f32_e32 v108, v6
	v_fmamk_f32 v6, v7, 0x3e0293ee, v111
	v_exp_f32_e32 v110, v4
	v_fmac_f32_e32 v111, 0x3e0293ee, v5
	v_pk_add_f32 v[4:5], v[92:93], 0 op_sel_hi:[1,0]
	v_exp_f32_e32 v14, v14
	v_exp_f32_e32 v15, v15
	v_pk_add_f32 v[4:5], v[82:83], v[4:5]
	v_exp_f32_e32 v103, v99
	v_pk_add_f32 v[4:5], v[94:95], v[4:5]
	v_exp_f32_e32 v101, v12
	v_pk_add_f32 v[4:5], v[16:17], v[4:5]
	v_exp_f32_e32 v98, v98
	v_exp_f32_e32 v99, v90
	v_pk_add_f32 v[4:5], v[96:97], v[4:5]
	v_exp_f32_e32 v105, v10
	v_pk_add_f32 v[4:5], v[14:15], v[4:5]
	v_exp_f32_e32 v88, v88
	v_exp_f32_e32 v89, v89
	v_pk_add_f32 v[4:5], v[102:103], v[4:5]
	v_exp_f32_e32 v107, v8
	v_pk_add_f32 v[4:5], v[100:101], v[4:5]
	v_exp_f32_e32 v86, v86
	v_exp_f32_e32 v87, v87
	v_pk_add_f32 v[4:5], v[98:99], v[4:5]
	v_exp_f32_e32 v109, v6
	v_pk_add_f32 v[4:5], v[104:105], v[4:5]
	v_exp_f32_e32 v84, v84
	v_exp_f32_e32 v85, v85
	v_pk_add_f32 v[4:5], v[88:89], v[4:5]
	v_exp_f32_e32 v111, v111
	v_pk_add_f32 v[4:5], v[106:107], v[4:5]
	v_cvt_pk_f16_f32 v6, v96, v97
	v_pk_add_f32 v[4:5], v[86:87], v[4:5]
	v_cvt_pk_f16_f32 v7, v102, v103
	v_pk_add_f32 v[4:5], v[108:109], v[4:5]
	v_cvt_pk_f16_f32 v8, v98, v99
	v_pk_add_f32 v[4:5], v[84:85], v[4:5]
	v_cvt_pk_f16_f32 v9, v88, v89
	v_pk_add_f32 v[4:5], v[110:111], v[4:5]
	v_cvt_pk_f16_f32 v10, v86, v87
	v_pk_add_f32 v[4:5], v[4:5], v[4:5] op_sel:[0,1] op_sel_hi:[1,0]
	v_cvt_pk_f16_f32 v11, v84, v85
	v_mov_b32_e32 v5, v4
	s_nop 1
	v_permlane32_swap_b32_e32 v4, v5
	v_add_f32_e32 v196, v4, v5
	v_cvt_pk_f16_f32 v4, v92, v93
	v_cvt_pk_f16_f32 v5, v94, v95
	v_cvt_pk_f16_f32 v12, v82, v83
	v_cvt_pk_f16_f32 v13, v16, v17
	v_cvt_pk_f16_f32 v14, v14, v15
	v_cvt_pk_f16_f32 v15, v100, v101
	v_cvt_pk_f16_f32 v82, v104, v105
	v_cvt_pk_f16_f32 v83, v106, v107
	v_cvt_pk_f16_f32 v84, v108, v109
	v_cvt_pk_f16_f32 v85, v110, v111
	v_fmac_f32_e32 v196, v190, v91
	v_permlane32_swap_b32_e32 v4, v6
	v_permlane32_swap_b32_e32 v5, v7
	v_permlane32_swap_b32_e32 v8, v10
	v_permlane32_swap_b32_e32 v9, v11
	v_permlane32_swap_b32_e32 v12, v14
	v_permlane32_swap_b32_e32 v13, v15
	v_permlane32_swap_b32_e32 v82, v84
	v_permlane32_swap_b32_e32 v83, v85
	v_add_u32_e32 v2, v187, v2
	ds_read_b64_tr_b16 v[86:87], v2 offset:0
	ds_read_b64_tr_b16 v[88:89], v2 offset:0x800
	ds_read_b64_tr_b16 v[90:91], v2 offset:0x1000
	ds_read_b64_tr_b16 v[92:93], v2 offset:0x1800
	ds_read_b64_tr_b16 v[94:95], v2 offset:0x2000
	ds_read_b64_tr_b16 v[96:97], v2 offset:0x2800
	ds_read_b64_tr_b16 v[98:99], v2 offset:0x3000
	ds_read_b64_tr_b16 v[100:101], v2 offset:0x3800
	ds_read_b64_tr_b16 v[102:103], v2 offset:0x200
	ds_read_b64_tr_b16 v[104:105], v2 offset:0xa00
	ds_read_b64_tr_b16 v[106:107], v2 offset:0x1200
	ds_read_b64_tr_b16 v[108:109], v2 offset:0x1a00
	ds_read_b64_tr_b16 v[110:111], v2 offset:0x2200
	ds_read_b64_tr_b16 v[112:113], v2 offset:0x2a00
	ds_read_b64_tr_b16 v[190:191], v2 offset:0x3200
	ds_read_b64_tr_b16 v[192:193], v2 offset:0x3a00
	s_waitcnt lgkmcnt(8)
	s_nop 0
	v_mfma_f32_32x32x16_f16 v[66:81], v[4:7], v[86:89], v[66:81]
	v_mfma_f32_32x32x16_f16 v[66:81], v[8:11], v[90:93], v[66:81]
	v_mfma_f32_32x32x16_f16 v[66:81], v[12:15], v[94:97], v[66:81]
	v_mfma_f32_32x32x16_f16 v[66:81], v[82:85], v[98:101], v[66:81]
	ds_read_b64_tr_b16 v[86:87], v2 offset:0x400
	ds_read_b64_tr_b16 v[88:89], v2 offset:0xc00
	ds_read_b64_tr_b16 v[90:91], v2 offset:0x1400
	ds_read_b64_tr_b16 v[92:93], v2 offset:0x1c00
	ds_read_b64_tr_b16 v[94:95], v2 offset:0x2400
	ds_read_b64_tr_b16 v[96:97], v2 offset:0x2c00
	ds_read_b64_tr_b16 v[98:99], v2 offset:0x3400
	ds_read_b64_tr_b16 v[100:101], v2 offset:0x3c00
	s_waitcnt lgkmcnt(8)
	v_mfma_f32_32x32x16_f16 v[50:65], v[4:7], v[102:105], v[50:65]
	v_mfma_f32_32x32x16_f16 v[50:65], v[8:11], v[106:109], v[50:65]
	v_mfma_f32_32x32x16_f16 v[50:65], v[12:15], v[110:113], v[50:65]
	v_mfma_f32_32x32x16_f16 v[50:65], v[82:85], v[190:193], v[50:65]
	ds_read_b64_tr_b16 v[102:103], v2 offset:0x600
	ds_read_b64_tr_b16 v[104:105], v2 offset:0xe00
	ds_read_b64_tr_b16 v[106:107], v2 offset:0x1600
	ds_read_b64_tr_b16 v[108:109], v2 offset:0x1e00
	ds_read_b64_tr_b16 v[110:111], v2 offset:0x2600
	ds_read_b64_tr_b16 v[112:113], v2 offset:0x2e00
	ds_read_b64_tr_b16 v[192:193], v2 offset:0x3600
	ds_read_b64_tr_b16 v[194:195], v2 offset:0x3e00
	s_waitcnt lgkmcnt(8)
	v_mfma_f32_32x32x16_f16 v[34:49], v[4:7], v[86:89], v[34:49]
	v_mfma_f32_32x32x16_f16 v[34:49], v[8:11], v[90:93], v[34:49]
	v_mfma_f32_32x32x16_f16 v[34:49], v[12:15], v[94:97], v[34:49]
	v_mfma_f32_32x32x16_f16 v[34:49], v[82:85], v[98:101], v[34:49]
	s_waitcnt lgkmcnt(0)
	v_mfma_f32_32x32x16_f16 v[18:33], v[4:7], v[102:105], v[18:33]
	v_mov_b32_e32 v190, v196
	v_mfma_f32_32x32x16_f16 v[18:33], v[8:11], v[106:109], v[18:33]
	v_mfma_f32_32x32x16_f16 v[18:33], v[12:15], v[110:113], v[18:33]
	v_mfma_f32_32x32x16_f16 v[18:33], v[82:85], v[192:195], v[18:33]

; __device__ __forceinline__ void partialSM(f32x16& p0, f32x16& p1, float& m_reg, float& mn, float& alpha, const float sc, const float C2) {
;     ...
;     if (__builtin_expect(__all((pmax - m_reg) * sc <= 8.0f), 1)) { mn = m_reg; alpha = 1.f; }
;     else { mn = fmaxf(m_reg, pmax); alpha = __builtin_amdgcn_exp2f((m_reg - mn) * C2); m_reg = mn; }
.Lslc_slow:
	v_max_f32_e32 v92, v189, v91
	v_sub_f32_e32 v91, v189, v92
	v_mul_f32_e32 v91, 0x3e0293ee, v91
	v_exp_f32_e32 v91, v91
	v_mov_b32_e32 v189, v92
	s_nop 0
	v_cmp_gt_f32_e32 vcc, 1.0, v91
	s_cbranch_vccz .Lslc_fast
	s_and_saveexec_b64 s[10:11], s[0:1]
	ds_write_b32 v178, v91 offset:128
	s_or_b64 exec, exec, s[10:11]
	s_waitcnt lgkmcnt(0)
	ds_read_b128 v[94:97], v1 offset:224
	ds_read_b128 v[104:107], v1 offset:192
	ds_read_b128 v[108:111], v1 offset:160
	ds_read_b128 v[194:197], v1 offset:128
	s_waitcnt lgkmcnt(3)
	v_pk_mul_f32 v[80:81], v[80:81], v[96:97]
	s_waitcnt lgkmcnt(2)
	v_pk_mul_f32 v[76:77], v[76:77], v[106:107]
	s_waitcnt lgkmcnt(1)
	v_pk_mul_f32 v[72:73], v[72:73], v[110:111]
	s_waitcnt lgkmcnt(0)
	v_pk_mul_f32 v[68:69], v[68:69], v[196:197]
	v_pk_mul_f32 v[78:79], v[78:79], v[94:95]
	v_pk_mul_f32 v[74:75], v[74:75], v[104:105]
	v_pk_mul_f32 v[70:71], v[70:71], v[108:109]
	v_pk_mul_f32 v[66:67], v[66:67], v[194:195]
	v_pk_mul_f32 v[64:65], v[64:65], v[96:97]
	v_pk_mul_f32 v[60:61], v[60:61], v[106:107]
	v_pk_mul_f32 v[56:57], v[56:57], v[110:111]
	v_pk_mul_f32 v[52:53], v[52:53], v[196:197]
	v_pk_mul_f32 v[62:63], v[62:63], v[94:95]
	v_pk_mul_f32 v[58:59], v[58:59], v[104:105]
	v_pk_mul_f32 v[54:55], v[54:55], v[108:109]
	v_pk_mul_f32 v[50:51], v[50:51], v[194:195]
	v_pk_mul_f32 v[48:49], v[48:49], v[96:97]
	v_pk_mul_f32 v[44:45], v[44:45], v[106:107]
	v_pk_mul_f32 v[40:41], v[40:41], v[110:111]
	v_pk_mul_f32 v[36:37], v[36:37], v[196:197]
	v_pk_mul_f32 v[46:47], v[46:47], v[94:95]
	v_pk_mul_f32 v[42:43], v[42:43], v[104:105]
	v_pk_mul_f32 v[38:39], v[38:39], v[108:109]
	v_pk_mul_f32 v[34:35], v[34:35], v[194:195]
	v_pk_mul_f32 v[32:33], v[32:33], v[96:97]
	v_pk_mul_f32 v[28:29], v[28:29], v[106:107]
	v_pk_mul_f32 v[24:25], v[24:25], v[110:111]
	v_pk_mul_f32 v[20:21], v[20:21], v[196:197]
	v_pk_mul_f32 v[30:31], v[30:31], v[94:95]
	v_pk_mul_f32 v[26:27], v[26:27], v[104:105]
	v_pk_mul_f32 v[22:23], v[22:23], v[108:109]
	v_pk_mul_f32 v[18:19], v[18:19], v[194:195]
	s_branch .Lslc_fast

; __device__ __forceinline__ float max3f(float a, float b, float c) { return __builtin_fmaxf(__builtin_fmaxf(a, b), c); }
; __device__ __forceinline__ void partialSM(f32x16& p0, f32x16& p1, float& m_reg, float& mn, float& alpha, const float sc, const float C2) {
;     float pmax = max3f(p0[0], p0[1], p0[2]);
; #pragma unroll
;     for (int r = 3; r < 15; r += 2) pmax = max3f(pmax, p0[r], p0[r + 1]);
;     pmax = max3f(pmax, p0[15], p1[0]);
; #pragma unroll
;     for (int r = 1; r < 15; r += 2) pmax = max3f(pmax, p1[r], p1[r + 1]);
;     pmax = fmaxf(pmax, p1[15]);
;     { auto rr = __builtin_amdgcn_permlane32_swap(__float_as_uint(pmax), __float_as_uint(pmax), false, false);
;       pmax = fmaxf(__uint_as_float(rr[0]), __uint_as_float(rr[1])); }
;     if (__builtin_expect(__all((pmax - m_reg) * sc <= 8.0f), 1)) { mn = m_reg; alpha = 1.f; }
;     else { mn = fmaxf(m_reg, pmax); alpha = __builtin_amdgcn_exp2f((m_reg - mn) * C2); m_reg = mn; }
.LBB0_5011:
	s_nop 8
	v_max_f32_e32 v4, v98, v99
	v_max3_f32 v4, v4, v100, v101
	v_max3_f32 v4, v4, v102, v103
	v_max3_f32 v4, v4, v104, v105
	v_max3_f32 v4, v4, v106, v107
	v_max3_f32 v4, v4, v108, v109
	v_max3_f32 v4, v4, v110, v111
	v_max3_f32 v4, v4, v112, v113
	v_max3_f32 v4, v4, v82, v83
	v_max3_f32 v4, v4, v84, v85
	v_max3_f32 v4, v4, v86, v87
	v_max3_f32 v4, v4, v88, v89
	v_max3_f32 v4, v4, v90, v91
	v_max3_f32 v4, v4, v92, v93
	v_max3_f32 v4, v4, v94, v95
	v_max3_f32 v4, v4, v96, v97
	v_mov_b32_e32 v5, v4
	s_nop 1
	v_permlane32_swap_b32_e32 v4, v5
	v_max_f32_e32 v4, v4, v5
	v_sub_f32_e32 v5, v4, v182
	v_mul_f32_e32 v5, 0x3db504f3, v5
	v_cmp_ge_f32_e32 vcc, s87, v5
	v_mov_b32_e32 v188, 1.0
	s_cmp_eq_u64 vcc, exec
	s_cbranch_scc0 .Lwin_slow
; #define FA_SBAR() __builtin_amdgcn_sched_barrier(0)
; #define FA_RD8(S, d0) do { constexpr int b_ = v_rd_off(d0, 0, 0); FA_TRRD(S##l0, b_); FA_TRRD(S##h0, b_ + 2048); FA_TRRD(S##l1, b_ + 4096); FA_TRRD(S##h1, b_ + 6144); FA_TRRD(S##l2, b_ + 8192); FA_TRRD(S##h2, b_ + 10240); FA_TRRD(S##l3, b_ + 12288); FA_TRRD(S##h3, b_ + 14336); } while (0)
; __device__ __forceinline__ void partialSM(f32x16& p0, f32x16& p1, float& m_reg, float& mn, float& alpha, const float sc, const float C2) {
;     ...
;     const float mnL = -mn * C2;
; #pragma unroll
;     for (int r = 0; r < 16; ++r) p0[r] = __builtin_amdgcn_exp2f(fmaf(p0[r], C2, mnL));
; #pragma unroll
;     for (int r = 0; r < 16; ++r) p1[r] = __builtin_amdgcn_exp2f(fmaf(p1[r], C2, mnL));
; }
; __device__ __forceinline__ void finishSM(const f32x16& p0, const f32x16& p1, float alpha, float& l_reg, half8& pa0, half8& pa1, half8& pa2, half8& pa3) {
;     f32x2 s2 = {0.f, 0.f};
; #pragma unroll
;     for (int r = 0; r < 16; r += 2) { s2 += (f32x2){p0[r], p0[r + 1]}; s2 += (f32x2){p1[r], p1[r + 1]}; }
;     float ps = s2[0] + s2[1];
;     { auto rr = __builtin_amdgcn_permlane32_swap(__float_as_uint(ps), __float_as_uint(ps), false, false);
;       ps = __uint_as_float(rr[0]) + __uint_as_float(rr[1]); }
;     l_reg = l_reg * alpha + ps;
;     ...
;     FA_PK4(p0, 0, pa0); FA_PK4(p0, 8, pa1); FA_PK4(p1, 0, pa2); FA_PK4(p1, 8, pa3);
;     ...
; }
; __device__ __forceinline__ void pv_tile2(f32x16* o, int vb0, half8 pa0, half8 pa1, half8 pa2, half8 pa3) {
;     ...
;     s16x4 al0, al1, al2, al3, ah0, ah1, ah2, ah3, bl0, bl1, bl2, bl3, bh0, bh1, bh2, bh3;
;     FA_RD8(a, 0);
;     FA_RD8(b, 1); asm volatile("s_waitcnt lgkmcnt(8)" ::: "memory"); FA_SBAR(); FA_MM4(a, 0); FA_SBAR();
;     FA_RD8(a, 2); asm volatile("s_waitcnt lgkmcnt(8)" ::: "memory"); FA_SBAR(); FA_MM4(b, 1); FA_SBAR();
;     FA_RD8(b, 3); asm volatile("s_waitcnt lgkmcnt(8)" ::: "memory"); FA_SBAR(); FA_MM4(a, 2); FA_SBAR();
;     asm volatile("s_waitcnt lgkmcnt(0)" ::: "memory"); FA_SBAR(); FA_MM4(b, 3);
;     ...
; }
.Lwin_fast:
.LBB0_5015:
	v_mul_f32_e32 v5, 0xbe0293ee, v182
	v_fmamk_f32 v6, v98, 0x3e0293ee, v5
	v_fmamk_f32 v7, v99, 0x3e0293ee, v5
	v_exp_f32_e32 v6, v6
	v_exp_f32_e32 v7, v7
	v_fmamk_f32 v82, v82, 0x3e0293ee, v5
	v_fmamk_f32 v83, v83, 0x3e0293ee, v5
	v_fmamk_f32 v8, v100, 0x3e0293ee, v5
	v_fmamk_f32 v9, v101, 0x3e0293ee, v5
	v_exp_f32_e32 v82, v82
	v_exp_f32_e32 v83, v83
	v_exp_f32_e32 v8, v8
	v_exp_f32_e32 v9, v9
	v_fmamk_f32 v84, v84, 0x3e0293ee, v5
	v_fmamk_f32 v85, v85, 0x3e0293ee, v5
	v_fmamk_f32 v10, v102, 0x3e0293ee, v5
	v_fmamk_f32 v11, v103, 0x3e0293ee, v5
	v_exp_f32_e32 v84, v84
	v_exp_f32_e32 v85, v85
	v_exp_f32_e32 v10, v10
	v_exp_f32_e32 v11, v11
	v_fmamk_f32 v86, v86, 0x3e0293ee, v5
	v_fmamk_f32 v87, v87, 0x3e0293ee, v5
	v_pk_add_f32 v[102:103], v[6:7], 0 op_sel_hi:[1,0]
	v_fmamk_f32 v12, v104, 0x3e0293ee, v5
	v_fmamk_f32 v13, v105, 0x3e0293ee, v5
	v_exp_f32_e32 v86, v86
	v_exp_f32_e32 v87, v87
	v_pk_add_f32 v[102:103], v[82:83], v[102:103]
	v_exp_f32_e32 v12, v12
	v_exp_f32_e32 v13, v13
	v_fmamk_f32 v88, v88, 0x3e0293ee, v5
	v_fmamk_f32 v89, v89, 0x3e0293ee, v5
	v_pk_add_f32 v[102:103], v[8:9], v[102:103]
	v_fmamk_f32 v14, v106, 0x3e0293ee, v5
	v_fmamk_f32 v15, v107, 0x3e0293ee, v5
	v_exp_f32_e32 v88, v88
	v_exp_f32_e32 v89, v89
	v_pk_add_f32 v[102:103], v[84:85], v[102:103]
	v_exp_f32_e32 v14, v14
	v_exp_f32_e32 v15, v15
	v_fmamk_f32 v90, v90, 0x3e0293ee, v5
	v_fmamk_f32 v91, v91, 0x3e0293ee, v5
	v_pk_add_f32 v[102:103], v[10:11], v[102:103]
	v_fmamk_f32 v16, v108, 0x3e0293ee, v5
	v_fmamk_f32 v17, v109, 0x3e0293ee, v5
	v_exp_f32_e32 v90, v90
	v_exp_f32_e32 v91, v91
	v_pk_add_f32 v[102:103], v[86:87], v[102:103]
	v_exp_f32_e32 v16, v16
	v_exp_f32_e32 v17, v17
	v_fmamk_f32 v92, v92, 0x3e0293ee, v5
	v_fmamk_f32 v93, v93, 0x3e0293ee, v5
	v_pk_add_f32 v[102:103], v[12:13], v[102:103]
	v_fmamk_f32 v98, v110, 0x3e0293ee, v5
	v_fmamk_f32 v99, v111, 0x3e0293ee, v5
	v_exp_f32_e32 v92, v92
	v_exp_f32_e32 v93, v93
	v_pk_add_f32 v[102:103], v[88:89], v[102:103]
	v_exp_f32_e32 v98, v98
	v_exp_f32_e32 v99, v99
	v_fmamk_f32 v94, v94, 0x3e0293ee, v5
	v_fmamk_f32 v95, v95, 0x3e0293ee, v5
	v_pk_add_f32 v[102:103], v[14:15], v[102:103]
	v_fmamk_f32 v100, v112, 0x3e0293ee, v5
	v_fmamk_f32 v101, v113, 0x3e0293ee, v5
	v_exp_f32_e32 v94, v94
	v_exp_f32_e32 v95, v95
	v_pk_add_f32 v[102:103], v[90:91], v[102:103]
	v_exp_f32_e32 v100, v100
	v_exp_f32_e32 v101, v101
	v_fmamk_f32 v96, v96, 0x3e0293ee, v5
	v_fmac_f32_e32 v5, 0x3e0293ee, v97
	v_pk_add_f32 v[102:103], v[16:17], v[102:103]
	v_exp_f32_e32 v96, v96
	v_exp_f32_e32 v97, v5
	v_pk_add_f32 v[102:103], v[92:93], v[102:103]
	v_cvt_pk_f16_f32 v4, v6, v7
	v_pk_add_f32 v[102:103], v[98:99], v[102:103]
	v_cvt_pk_f16_f32 v5, v8, v9
	v_pk_add_f32 v[102:103], v[94:95], v[102:103]
	v_cvt_pk_f16_f32 v6, v10, v11
	v_pk_add_f32 v[102:103], v[100:101], v[102:103]
	v_cvt_pk_f16_f32 v7, v12, v13
	v_pk_add_f32 v[102:103], v[96:97], v[102:103]
	v_cvt_pk_f16_f32 v8, v14, v15
	v_pk_add_f32 v[102:103], v[102:103], v[102:103] op_sel:[0,1] op_sel_hi:[1,0]
	v_cvt_pk_f16_f32 v9, v16, v17
	v_mov_b32_e32 v103, v102
	v_cvt_pk_f16_f32 v10, v98, v99
	v_cvt_pk_f16_f32 v11, v100, v101
	v_permlane32_swap_b32_e32 v102, v103
	v_cvt_pk_f16_f32 v12, v82, v83
	v_add_f32_e32 v103, v102, v103
	v_cvt_pk_f16_f32 v13, v84, v85
	v_fma_f32 v183, v183, v188, v103
	v_cvt_pk_f16_f32 v14, v86, v87
	v_cvt_pk_f16_f32 v15, v88, v89
	v_cvt_pk_f16_f32 v82, v90, v91
	v_cvt_pk_f16_f32 v83, v92, v93
	v_cvt_pk_f16_f32 v84, v94, v95
	v_cvt_pk_f16_f32 v85, v96, v97
	v_permlane32_swap_b32_e32 v4, v6
	v_permlane32_swap_b32_e32 v5, v7
	v_permlane32_swap_b32_e32 v8, v10
	v_permlane32_swap_b32_e32 v9, v11
	v_permlane32_swap_b32_e32 v12, v14
	v_permlane32_swap_b32_e32 v13, v15
	v_permlane32_swap_b32_e32 v82, v84
	v_permlane32_swap_b32_e32 v83, v85
	v_add_u32_e32 v2, v180, v2
	ds_read_b64_tr_b16 v[86:87], v2 offset:0
	ds_read_b64_tr_b16 v[88:89], v2 offset:0x800
	ds_read_b64_tr_b16 v[90:91], v2 offset:0x1000
	ds_read_b64_tr_b16 v[92:93], v2 offset:0x1800
	ds_read_b64_tr_b16 v[94:95], v2 offset:0x2000
	ds_read_b64_tr_b16 v[96:97], v2 offset:0x2800
	ds_read_b64_tr_b16 v[98:99], v2 offset:0x3000
	ds_read_b64_tr_b16 v[100:101], v2 offset:0x3800
	ds_read_b64_tr_b16 v[102:103], v2 offset:0x200
	ds_read_b64_tr_b16 v[104:105], v2 offset:0xa00
	ds_read_b64_tr_b16 v[106:107], v2 offset:0x1200
	ds_read_b64_tr_b16 v[108:109], v2 offset:0x1a00
	ds_read_b64_tr_b16 v[110:111], v2 offset:0x2200
	ds_read_b64_tr_b16 v[112:113], v2 offset:0x2a00
	ds_read_b64_tr_b16 v[184:185], v2 offset:0x3200
	ds_read_b64_tr_b16 v[186:187], v2 offset:0x3a00
	s_waitcnt lgkmcnt(8)
	s_nop 0
	v_mfma_f32_32x32x16_f16 v[66:81], v[4:7], v[86:89], v[66:81]
	v_mfma_f32_32x32x16_f16 v[66:81], v[8:11], v[90:93], v[66:81]
	v_mfma_f32_32x32x16_f16 v[66:81], v[12:15], v[94:97], v[66:81]
	v_mfma_f32_32x32x16_f16 v[66:81], v[82:85], v[98:101], v[66:81]
	ds_read_b64_tr_b16 v[86:87], v2 offset:0x400
	ds_read_b64_tr_b16 v[88:89], v2 offset:0xc00
	ds_read_b64_tr_b16 v[90:91], v2 offset:0x1400
	ds_read_b64_tr_b16 v[92:93], v2 offset:0x1c00
	ds_read_b64_tr_b16 v[94:95], v2 offset:0x2400
	ds_read_b64_tr_b16 v[96:97], v2 offset:0x2c00
	ds_read_b64_tr_b16 v[98:99], v2 offset:0x3400
	ds_read_b64_tr_b16 v[100:101], v2 offset:0x3c00
	s_waitcnt lgkmcnt(8)
	v_mfma_f32_32x32x16_f16 v[50:65], v[4:7], v[102:105], v[50:65]
	v_mfma_f32_32x32x16_f16 v[50:65], v[8:11], v[106:109], v[50:65]
	v_mfma_f32_32x32x16_f16 v[50:65], v[12:15], v[110:113], v[50:65]
	v_mfma_f32_32x32x16_f16 v[50:65], v[82:85], v[184:187], v[50:65]
	ds_read_b64_tr_b16 v[102:103], v2 offset:0x600
	ds_read_b64_tr_b16 v[104:105], v2 offset:0xe00
	ds_read_b64_tr_b16 v[106:107], v2 offset:0x1600
	ds_read_b64_tr_b16 v[108:109], v2 offset:0x1e00
	ds_read_b64_tr_b16 v[110:111], v2 offset:0x2600
	ds_read_b64_tr_b16 v[112:113], v2 offset:0x2e00
	ds_read_b64_tr_b16 v[184:185], v2 offset:0x3600
	ds_read_b64_tr_b16 v[186:187], v2 offset:0x3e00
	s_waitcnt lgkmcnt(8)
	v_mfma_f32_32x32x16_f16 v[34:49], v[4:7], v[86:89], v[34:49]
	v_mfma_f32_32x32x16_f16 v[34:49], v[8:11], v[90:93], v[34:49]
	v_mfma_f32_32x32x16_f16 v[34:49], v[12:15], v[94:97], v[34:49]
	v_mfma_f32_32x32x16_f16 v[34:49], v[82:85], v[98:101], v[34:49]
	s_waitcnt lgkmcnt(0)
	v_mfma_f32_32x32x16_f16 v[18:33], v[4:7], v[102:105], v[18:33]
	v_mfma_f32_32x32x16_f16 v[18:33], v[8:11], v[106:109], v[18:33]
	v_mfma_f32_32x32x16_f16 v[18:33], v[12:15], v[110:113], v[18:33]
	v_mfma_f32_32x32x16_f16 v[18:33], v[82:85], v[184:187], v[18:33]

; __device__ __forceinline__ void partialSM(f32x16& p0, f32x16& p1, float& m_reg, float& mn, float& alpha, const float sc, const float C2) {
;     ...
;     if (__builtin_expect(__all((pmax - m_reg) * sc <= 8.0f), 1)) { mn = m_reg; alpha = 1.f; }
;     else { mn = fmaxf(m_reg, pmax); alpha = __builtin_amdgcn_exp2f((m_reg - mn) * C2); m_reg = mn; }
.Lwin_slow:
	v_max_f32_e32 v5, v182, v4
	v_sub_f32_e32 v4, v182, v5
	v_mul_f32_e32 v4, 0x3e0293ee, v4
	v_exp_f32_e32 v4, v4
	v_mov_b32_e32 v182, v5
	v_mov_b32_e32 v188, v4
	v_cmp_gt_f32_e32 vcc, 1.0, v4
	s_cbranch_vccz .Lwin_fast
	s_and_saveexec_b64 s[12:13], s[0:1]
	ds_write_b32 v169, v4 offset:128
	s_or_b64 exec, exec, s[12:13]
	s_waitcnt lgkmcnt(0)
	ds_read_b128 v[6:9], v179 offset:224
	ds_read_b128 v[10:13], v179 offset:192
	ds_read_b128 v[14:17], v179 offset:160
	ds_read_b128 v[184:187], v179 offset:128
	s_waitcnt lgkmcnt(3)
	v_pk_mul_f32 v[80:81], v[80:81], v[8:9]
	s_waitcnt lgkmcnt(2)
	v_pk_mul_f32 v[76:77], v[76:77], v[12:13]
	s_waitcnt lgkmcnt(1)
	v_pk_mul_f32 v[72:73], v[72:73], v[16:17]
	s_waitcnt lgkmcnt(0)
	v_pk_mul_f32 v[68:69], v[68:69], v[186:187]
	v_pk_mul_f32 v[78:79], v[78:79], v[6:7]
	v_pk_mul_f32 v[74:75], v[74:75], v[10:11]
	v_pk_mul_f32 v[70:71], v[70:71], v[14:15]
	v_pk_mul_f32 v[66:67], v[66:67], v[184:185]
	v_pk_mul_f32 v[64:65], v[64:65], v[8:9]
	v_pk_mul_f32 v[60:61], v[60:61], v[12:13]
	v_pk_mul_f32 v[56:57], v[56:57], v[16:17]
	v_pk_mul_f32 v[52:53], v[52:53], v[186:187]
	v_pk_mul_f32 v[62:63], v[62:63], v[6:7]
	v_pk_mul_f32 v[58:59], v[58:59], v[10:11]
	v_pk_mul_f32 v[54:55], v[54:55], v[14:15]
	v_pk_mul_f32 v[50:51], v[50:51], v[184:185]
	v_pk_mul_f32 v[48:49], v[48:49], v[8:9]
	v_pk_mul_f32 v[44:45], v[44:45], v[12:13]
	v_pk_mul_f32 v[40:41], v[40:41], v[16:17]
	v_pk_mul_f32 v[36:37], v[36:37], v[186:187]
	v_pk_mul_f32 v[46:47], v[46:47], v[6:7]
	v_pk_mul_f32 v[42:43], v[42:43], v[10:11]
	v_pk_mul_f32 v[38:39], v[38:39], v[14:15]
	v_pk_mul_f32 v[34:35], v[34:35], v[184:185]
	v_pk_mul_f32 v[32:33], v[32:33], v[8:9]
	v_pk_mul_f32 v[28:29], v[28:29], v[12:13]
	v_pk_mul_f32 v[24:25], v[24:25], v[16:17]
	v_pk_mul_f32 v[20:21], v[20:21], v[186:187]
	v_pk_mul_f32 v[30:31], v[30:31], v[6:7]
	v_pk_mul_f32 v[26:27], v[26:27], v[10:11]
	v_pk_mul_f32 v[22:23], v[22:23], v[14:15]
	v_pk_mul_f32 v[18:19], v[18:19], v[184:185]
	s_branch .Lwin_fast
